# scan: next staging loads issued before the chunk barrier (in its wait shadow) instead of after it
# speedup vs baseline: 1.0101x; 1.0101x over previous
; DI void scan_task(const Params& p, int l, int isP, int b, int h, int rg, char* smem, const bool dry) {
;     ...
;   auto gload = [&](int c) {
;     const int tk = tokbase + c * 32;
;     rd0 = *(const float4*)(p.R + (size_t)(tk + ds) * RS + h * 64 + dj * 4);
;     rd1 = *(const float4*)(p.R + (size_t)(tk + 16 + ds) * RS + h * 64 + dj * 4);
;     const bf16_t* rb = (const bf16_t*)(p.R + (size_t)(tk + lst) * RS + 512) + h * 64 + lch * 8;
;     qr = *(const uint4*)(rb);
;     qk = *(const uint4*)(rb + 512);
;     qa = *(const uint4*)(rb + 1536);
;     qb = *(const uint4*)(rb + 2048);
;     if (tid < 64) {
;       const int s = tid >> 1, half = tid & 1;
;       rv = *(const uint4*)((const bf16_t*)(p.R + (size_t)(tk + s) * RS + 512) + 1024 + h * 64 + rg * 16 + half * 8);
;     }
;   };
;     ...
;   auto sstore = [&](int bi) {
;     char* bb = smem + bi * BUFB;
;     *(float4*)(bb + (ds * 64 + dj * 4) * 4) = rd0;
;     *(float4*)(bb + ((16 + ds) * 64 + dj * 4) * 4) = rd1;
;     {
;       CVT8(qa, alo, ahi)
;       float* d = (float*)(bb + 8192) + lst * 64 + lch * 8;
;       *(float4*)d = alo; *(float4*)(d + 4) = ahi;
;     }
;     {
;       CVT8(qb, blo, bhi)
;       float* d = (float*)(bb + 16384) + lst * 64 + lch * 8;
;       *(float4*)d = blo; *(float4*)(d + 4) = bhi;
;     }
;     *(uint4*)(bb + 24576 + (lst * 64 + lch * 8) * 2) = qr;
;     *(uint4*)(bb + 28672 + (lst * 64 + lch * 8) * 2) = qk;
;     if (tid < 64) {
;       const int s = tid >> 1, half = tid & 1;
;       CVT8(rv, vlo, vhi)
;       float* d = (float*)(bb + 32768) + s * 16 + half * 8;
;     ...
;   __syncthreads();
;   gload(0);
;   sstore(0);
;   __syncthreads();
;   for (int c = 0; c < nch; c++) {
;     const bool more = c + 1 < nch;
;     if (more) gload(c + 1);
;     const char* bb = smem + (c & 1) * BUFB;
;     const float* fw = (const float*)bb + jq * 4;
;     const float* fa = (const float*)(bb + 8192) + jq * 4;
;     const float* fb = (const float*)(bb + 16384) + jq * 4;
;     const char* pr = bb + 24576 + jq * 8;
;     const char* pk = bb + 28672 + jq * 8;
;     const float* vb = (const float*)(bb + 32768) + wave * 4 + g4;
;     float* yo = p.yscan + (size_t)(tokbase + c * 32 + jq) * 512 + h * 64 + i;
;     float ykeep0 = 0.f, ykeep1 = 0.f, yprev = 0.f;
;     f32x4 w4 = *(const f32x4*)fw, a4 = *(const f32x4*)fa, b4 = *(const f32x4*)fb;
;     uint2 ur = *(const uint2*)pr, uk = *(const uint2*)pk;
.Lscan_nostate:
	v_mov_b32_e32 v59, v69
	v_lshrrev_b32_e32 v66, 6, v182
	s_nop 0
	v_readfirstlane_b32 s28, v66
	s_setprio 3
	s_barrier
	global_load_dwordx4 v[84:87], v80, s[12:13]
	global_load_dwordx2 v[88:89], v81, s[12:13] offset:-1024
	global_load_dwordx2 v[90:91], v81, s[12:13]
	global_load_dwordx2 v[92:93], v81, s[12:13] offset:2048
	global_load_dwordx2 v[94:95], v81, s[12:13] offset:3072
	global_load_ushort v96, v82, s[12:13]
	s_add_u32 s12, s12, 0x1c000
	s_addc_u32 s13, s13, 0
	global_load_dwordx4 v[100:103], v80, s[12:13]
	global_load_dwordx2 v[104:105], v81, s[12:13] offset:-1024
	global_load_dwordx2 v[106:107], v81, s[12:13]
	global_load_dwordx2 v[108:109], v81, s[12:13] offset:2048
	global_load_dwordx2 v[98:99], v81, s[12:13] offset:3072
	global_load_ushort v97, v82, s[12:13]
	s_add_u32 s12, s12, 0x1c000
	s_addc_u32 s13, s13, 0
	s_waitcnt vmcnt(6)
	ds_write_b128 v78, v[84:87] offset:0
	v_lshlrev_b32_e32 v8, 16, v92
	v_and_b32_e32 v9, 0xffff0000, v92
	v_lshlrev_b32_e32 v10, 16, v93
	v_and_b32_e32 v11, 0xffff0000, v93
	ds_write_b128 v78, v[8:11] offset:4096
	v_lshlrev_b32_e32 v12, 16, v94
	v_and_b32_e32 v13, 0xffff0000, v94
	v_lshlrev_b32_e32 v14, 16, v95
	v_and_b32_e32 v15, 0xffff0000, v95
	ds_write_b128 v78, v[12:15] offset:8192
	v_lshlrev_b32_e32 v16, 16, v88
	v_and_b32_e32 v17, 0xffff0000, v88
	v_lshlrev_b32_e32 v18, 16, v89
	v_and_b32_e32 v19, 0xffff0000, v89
	ds_write_b128 v78, v[16:19] offset:12288
	v_lshlrev_b32_e32 v20, 16, v90
	v_and_b32_e32 v21, 0xffff0000, v90
	v_lshlrev_b32_e32 v22, 16, v91
	v_and_b32_e32 v23, 0xffff0000, v91
	ds_write_b128 v78, v[20:23] offset:16384
	v_lshlrev_b32_e32 v24, 16, v96
	ds_write_b32 v79, v24 offset:20480
	global_load_dwordx4 v[84:87], v80, s[12:13]
	global_load_dwordx2 v[88:89], v81, s[12:13] offset:-1024
	global_load_dwordx2 v[90:91], v81, s[12:13]
	global_load_dwordx2 v[92:93], v81, s[12:13] offset:2048
	global_load_dwordx2 v[94:95], v81, s[12:13] offset:3072
	global_load_ushort v96, v82, s[12:13]
	s_add_u32 s12, s12, 0x1c000
	s_addc_u32 s13, s13, 0
	s_mov_b32 s22, 1
	s_waitcnt lgkmcnt(0)
	s_barrier
	s_cmp_eq_u32 s28, 0
	s_cbranch_scc1 .Lstgs
	s_nop 5
	s_cmp_eq_u32 s28, 1
	s_cbranch_scc1 .Lstgs
	s_nop 5
	s_cmp_eq_u32 s28, 2
	s_cbranch_scc1 .Lstgs
	s_nop 5

; DI void scan_task(const Params& p, int l, int isP, int b, int h, int rg, char* smem, const bool dry) {
;     ...
;   for (int c = 0; c < nch; c++) {
;     const bool more = c + 1 < nch;
;     if (more) gload(c + 1);
;     const char* bb = smem + (c & 1) * BUFB;
;     const float* fw = (const float*)bb + jq * 4;
;     const float* fa = (const float*)(bb + 8192) + jq * 4;
;     const float* fb = (const float*)(bb + 16384) + jq * 4;
;     const char* pr = bb + 24576 + jq * 8;
;     const char* pk = bb + 28672 + jq * 8;
;     const float* vb = (const float*)(bb + 32768) + wave * 4 + g4;
;     float* yo = p.yscan + (size_t)(tokbase + c * 32 + jq) * 512 + h * 64 + i;
;     float ykeep0 = 0.f, ykeep1 = 0.f, yprev = 0.f;
;     f32x4 w4 = *(const f32x4*)fw, a4 = *(const f32x4*)fa, b4 = *(const f32x4*)fb;
;     uint2 ur = *(const uint2*)pr, uk = *(const uint2*)pk;
;     float v = vb[0];
; #pragma unroll
;     for (int s = 0; s < 32; s++) {
;       f32x4 w4n = w4, a4n = a4, b4n = b4;
;       uint2 urn = ur, ukn = uk;
;       float vn = v;
;       if (s < 31) {
;         w4n = *(const f32x4*)(fw + (s + 1) * 64);
;         a4n = *(const f32x4*)(fa + (s + 1) * 64);
;         b4n = *(const f32x4*)(fb + (s + 1) * 64);
;         urn = *(const uint2*)(pr + (s + 1) * 128);
;         ukn = *(const uint2*)(pk + (s + 1) * 128);
;         vn = vb[(s + 1) * 16];
;       }
;       __builtin_amdgcn_sched_barrier(0);
;       const f32x2 klo = {__uint_as_float(uk.x << 16), __uint_as_float(uk.x & 0xFFFF0000u)};
;       const f32x2 khi = {__uint_as_float(uk.y << 16), __uint_as_float(uk.y & 0xFFFF0000u)};
;       const f32x2 rlo = {__uint_as_float(ur.x << 16), __uint_as_float(ur.x & 0xFFFF0000u)};
;       const f32x2 rhi = {__uint_as_float(ur.y << 16), __uint_as_float(ur.y & 0xFFFF0000u)};
;       const f32x2 vv = {v, v};
;       const f32x2 t = Sa * a4.lo + Sb * a4.hi;
;       const f32x2 na = Sa * w4.lo + vv * klo;
;       const f32x2 nb = Sb * w4.hi + vv * khi;
;       float sa = t.x + t.y;
;       float yp = yprev;
;       rowsum16x2(sa, yp);
;       if (s >= 1 && s <= 16) ykeep0 = (jq == s - 1) ? yp : ykeep0;
;       if (s >= 17) ykeep1 = (jq == s - 17) ? yp : ykeep1;
;       const f32x2 sv = {sa, sa};
;       Sa = na + sv * b4.lo;
;       Sb = nb + sv * b4.hi;
;       const f32x2 yy = Sa * rlo + Sb * rhi;
;       yprev = yy.x + yy.y;
.Lscan_loop:
.Lscan_bodyA:
	s_waitcnt lgkmcnt(6)
	ds_read_b128 v[228:231], v76 offset:4608
	ds_read_b128 v[240:243], v76 offset:16896
	ds_read_b128 v[224:227], v76 offset:512
	ds_read_b128 v[232:235], v76 offset:8704
	ds_read_b128 v[236:239], v76 offset:12800
	v_pk_mul_f32 v[56:57], v[4:5], v[12:13]
	v_pk_fma_f32 v[56:57], v[6:7], v[14:15], v[56:57]
	v_add_f32_e32 v58, v56, v57
	v_pk_mul_f32 v[60:61], v[48:49], v[24:25] op_sel_hi:[0,1]
	v_pk_mul_f32 v[62:63], v[48:49], v[26:27] op_sel_hi:[0,1]
	v_add_f32_dpp v58, v58, v58 quad_perm:[1,0,3,2] row_mask:0xf bank_mask:0xf bound_ctrl:1
	v_pk_fma_f32 v[60:61], v[4:5], v[8:9], v[60:61]
	v_pk_fma_f32 v[62:63], v[6:7], v[10:11], v[62:63]
	v_add_f32_dpp v58, v58, v58 quad_perm:[2,3,0,1] row_mask:0xf bank_mask:0xf bound_ctrl:1
	s_nop 1
	v_add_f32_dpp v58, v58, v58 row_half_mirror row_mask:0xf bank_mask:0xf bound_ctrl:1
	s_nop 1
	v_add_f32_dpp v58, v58, v58 row_mirror row_mask:0xf bank_mask:0xf bound_ctrl:1
	v_pk_fma_f32 v[4:5], v[58:59], v[16:17], v[60:61] op_sel_hi:[0,1,1]
	v_pk_fma_f32 v[6:7], v[58:59], v[18:19], v[62:63] op_sel_hi:[0,1,1]
	s_waitcnt lgkmcnt(6)
	ds_read_b128 v[12:15], v76 offset:4864
	ds_read_b128 v[24:27], v76 offset:17152
	ds_read_b128 v[8:11], v76 offset:768
	ds_read_b128 v[16:19], v76 offset:8960
	ds_read_b128 v[52:55], v77 offset:20496
	v_pk_mul_f32 v[56:57], v[4:5], v[32:33]
	v_pk_mul_f32 v[64:65], v[4:5], v[20:21]
	v_pk_fma_f32 v[56:57], v[6:7], v[34:35], v[56:57]
	v_pk_fma_f32 v[64:65], v[6:7], v[22:23], v[64:65]
	v_add_f32_e32 v58, v56, v57
	v_pk_mul_f32 v[60:61], v[48:49], v[44:45] op_sel:[1,0] op_sel_hi:[1,1]
	v_pk_mul_f32 v[62:63], v[48:49], v[46:47] op_sel:[1,0] op_sel_hi:[1,1]
	v_add_f32_dpp v58, v58, v58 quad_perm:[1,0,3,2] row_mask:0xf bank_mask:0xf bound_ctrl:1
	v_pk_fma_f32 v[60:61], v[4:5], v[28:29], v[60:61]
	v_add_f32_e32 v66, v64, v65
	v_add_f32_dpp v58, v58, v58 quad_perm:[2,3,0,1] row_mask:0xf bank_mask:0xf bound_ctrl:1
	v_pk_fma_f32 v[62:63], v[6:7], v[30:31], v[62:63]
	s_nop 0
	v_add_f32_dpp v58, v58, v58 row_half_mirror row_mask:0xf bank_mask:0xf bound_ctrl:1
	ds_read_b128 v[20:23], v76 offset:13056
	s_nop 0
	v_add_f32_dpp v58, v58, v58 row_mirror row_mask:0xf bank_mask:0xf bound_ctrl:1
	v_pk_fma_f32 v[4:5], v[58:59], v[36:37], v[60:61] op_sel_hi:[0,1,1]
	v_pk_fma_f32 v[6:7], v[58:59], v[38:39], v[62:63] op_sel_hi:[0,1,1]
	s_waitcnt lgkmcnt(7)
	ds_read_b128 v[32:35], v76 offset:5120
	ds_read_b128 v[44:47], v76 offset:17408
	ds_read_b128 v[28:31], v76 offset:1024
	ds_read_b128 v[36:39], v76 offset:9216
	v_pk_mul_f32 v[56:57], v[4:5], v[228:229]
	v_pk_mul_f32 v[64:65], v[4:5], v[40:41]
	v_pk_fma_f32 v[56:57], v[6:7], v[230:231], v[56:57]
	v_pk_fma_f32 v[64:65], v[6:7], v[42:43], v[64:65]
	v_add_f32_e32 v58, v56, v57
	v_pk_mul_f32 v[60:61], v[50:51], v[240:241] op_sel_hi:[0,1]
	v_pk_mul_f32 v[62:63], v[50:51], v[242:243] op_sel_hi:[0,1]
	v_add_f32_dpp v58, v58, v58 quad_perm:[1,0,3,2] row_mask:0xf bank_mask:0xf bound_ctrl:1
	v_pk_fma_f32 v[60:61], v[4:5], v[224:225], v[60:61]
	v_add_f32_e32 v67, v64, v65
	v_add_f32_dpp v58, v58, v58 quad_perm:[2,3,0,1] row_mask:0xf bank_mask:0xf bound_ctrl:1
	v_pk_fma_f32 v[62:63], v[6:7], v[226:227], v[62:63]
	v_add_f32_dpp v68, v66, v66 row_mirror row_mask:0xf bank_mask:0x3
	v_add_f32_dpp v58, v58, v58 row_half_mirror row_mask:0xf bank_mask:0xf bound_ctrl:1
	s_nop 0
	v_add_f32_dpp v68, v67, v67 row_mirror row_mask:0xf bank_mask:0xc
	ds_read_b128 v[40:43], v76 offset:13312
	v_add_f32_dpp v58, v58, v58 row_mirror row_mask:0xf bank_mask:0xf bound_ctrl:1
	v_pk_fma_f32 v[4:5], v[58:59], v[232:233], v[60:61] op_sel_hi:[0,1,1]
	v_pk_fma_f32 v[6:7], v[58:59], v[234:235], v[62:63] op_sel_hi:[0,1,1]
	s_waitcnt lgkmcnt(7)
	ds_read_b128 v[228:231], v76 offset:5376
	ds_read_b128 v[240:243], v76 offset:17664
	ds_read_b128 v[224:227], v76 offset:1280
	ds_read_b128 v[232:235], v76 offset:9472
	v_pk_mul_f32 v[56:57], v[4:5], v[12:13]
	v_pk_mul_f32 v[64:65], v[4:5], v[236:237]
	v_pk_fma_f32 v[56:57], v[6:7], v[14:15], v[56:57]
	v_pk_fma_f32 v[64:65], v[6:7], v[238:239], v[64:65]
	v_add_f32_e32 v58, v56, v57
	v_pk_mul_f32 v[60:61], v[50:51], v[24:25] op_sel:[1,0] op_sel_hi:[1,1]
	v_pk_mul_f32 v[62:63], v[50:51], v[26:27] op_sel:[1,0] op_sel_hi:[1,1]
	v_add_f32_dpp v58, v58, v58 quad_perm:[1,0,3,2] row_mask:0xf bank_mask:0xf bound_ctrl:1
	v_pk_fma_f32 v[60:61], v[4:5], v[8:9], v[60:61]
	v_add_f32_e32 v66, v64, v65
	v_add_f32_dpp v58, v58, v58 quad_perm:[2,3,0,1] row_mask:0xf bank_mask:0xf bound_ctrl:1
	v_pk_fma_f32 v[62:63], v[6:7], v[10:11], v[62:63]
	s_nop 0
	v_add_f32_dpp v58, v58, v58 row_half_mirror row_mask:0xf bank_mask:0xf bound_ctrl:1
	ds_read_b128 v[236:239], v76 offset:13568
	s_nop 0
	v_add_f32_dpp v58, v58, v58 row_mirror row_mask:0xf bank_mask:0xf bound_ctrl:1
	v_pk_fma_f32 v[4:5], v[58:59], v[16:17], v[60:61] op_sel_hi:[0,1,1]
	v_pk_fma_f32 v[6:7], v[58:59], v[18:19], v[62:63] op_sel_hi:[0,1,1]
	s_waitcnt lgkmcnt(6)
	ds_read_b128 v[12:15], v76 offset:5632
	ds_read_b128 v[24:27], v76 offset:17920
	ds_read_b128 v[8:11], v76 offset:1536
	ds_read_b128 v[16:19], v76 offset:9728
	v_pk_mul_f32 v[56:57], v[4:5], v[32:33]
	v_pk_mul_f32 v[64:65], v[4:5], v[20:21]
	v_pk_fma_f32 v[56:57], v[6:7], v[34:35], v[56:57]
	v_pk_fma_f32 v[64:65], v[6:7], v[22:23], v[64:65]
	v_add_f32_e32 v58, v56, v57
	v_pk_mul_f32 v[60:61], v[52:53], v[44:45] op_sel_hi:[0,1]
	v_pk_mul_f32 v[62:63], v[52:53], v[46:47] op_sel_hi:[0,1]
	v_add_f32_dpp v58, v58, v58 quad_perm:[1,0,3,2] row_mask:0xf bank_mask:0xf bound_ctrl:1
	v_pk_fma_f32 v[60:61], v[4:5], v[28:29], v[60:61]
	v_add_f32_e32 v67, v64, v65
	v_add_f32_dpp v58, v58, v58 quad_perm:[2,3,0,1] row_mask:0xf bank_mask:0xf bound_ctrl:1
	v_pk_fma_f32 v[62:63], v[6:7], v[30:31], v[62:63]
	v_add_f32_dpp v69, v66, v66 row_mirror row_mask:0xf bank_mask:0x3
	v_add_f32_dpp v58, v58, v58 row_half_mirror row_mask:0xf bank_mask:0xf bound_ctrl:1
	s_nop 0
	v_add_f32_dpp v69, v67, v67 row_mirror row_mask:0xf bank_mask:0xc
	ds_read_b128 v[20:23], v76 offset:13824
	v_add_f32_dpp v58, v58, v58 row_mirror row_mask:0xf bank_mask:0xf bound_ctrl:1
	v_pk_fma_f32 v[4:5], v[58:59], v[36:37], v[60:61] op_sel_hi:[0,1,1]
	v_pk_fma_f32 v[6:7], v[58:59], v[38:39], v[62:63] op_sel_hi:[0,1,1]
	s_waitcnt lgkmcnt(6)
; DI void scan_task(const Params& p, int l, int isP, int b, int h, int rg, char* smem, const bool dry) {
;     ...
;     for (int s = 0; s < 32; s++) {
;       f32x4 w4n = w4, a4n = a4, b4n = b4;
;       uint2 urn = ur, ukn = uk;
;       float vn = v;
;       if (s < 31) {
;         w4n = *(const f32x4*)(fw + (s + 1) * 64);
;         a4n = *(const f32x4*)(fa + (s + 1) * 64);
;         b4n = *(const f32x4*)(fb + (s + 1) * 64);
;         urn = *(const uint2*)(pr + (s + 1) * 128);
;         ukn = *(const uint2*)(pk + (s + 1) * 128);
;         vn = vb[(s + 1) * 16];
;       }
;       __builtin_amdgcn_sched_barrier(0);
;       const f32x2 klo = {__uint_as_float(uk.x << 16), __uint_as_float(uk.x & 0xFFFF0000u)};
;       const f32x2 khi = {__uint_as_float(uk.y << 16), __uint_as_float(uk.y & 0xFFFF0000u)};
;       const f32x2 rlo = {__uint_as_float(ur.x << 16), __uint_as_float(ur.x & 0xFFFF0000u)};
;       const f32x2 rhi = {__uint_as_float(ur.y << 16), __uint_as_float(ur.y & 0xFFFF0000u)};
;       const f32x2 vv = {v, v};
;       const f32x2 t = Sa * a4.lo + Sb * a4.hi;
;       const f32x2 na = Sa * w4.lo + vv * klo;
;       const f32x2 nb = Sb * w4.hi + vv * khi;
;       float sa = t.x + t.y;
;       float yp = yprev;
;       rowsum16x2(sa, yp);
;       if (s >= 1 && s <= 16) ykeep0 = (jq == s - 1) ? yp : ykeep0;
;       if (s >= 17) ykeep1 = (jq == s - 17) ? yp : ykeep1;
;       const f32x2 sv = {sa, sa};
;       Sa = na + sv * b4.lo;
;       Sb = nb + sv * b4.hi;
;       const f32x2 yy = Sa * rlo + Sb * rhi;
;       yprev = yy.x + yy.y;
;       w4 = w4n; a4 = a4n; b4 = b4n; ur = urn; uk = ukn; v = vn;
;     }
	ds_read_b128 v[32:35], v76 offset:5888
	ds_read_b128 v[44:47], v76 offset:18176
	ds_read_b128 v[28:31], v76 offset:1792
	ds_read_b128 v[36:39], v76 offset:9984
	ds_read_b128 v[48:51], v77 offset:20512
	v_pk_mul_f32 v[56:57], v[4:5], v[228:229]
	v_pk_mul_f32 v[64:65], v[4:5], v[40:41]
	v_pk_fma_f32 v[56:57], v[6:7], v[230:231], v[56:57]
	v_pk_fma_f32 v[64:65], v[6:7], v[42:43], v[64:65]
	v_add_f32_e32 v58, v56, v57
	v_pk_mul_f32 v[60:61], v[52:53], v[240:241] op_sel:[1,0] op_sel_hi:[1,1]
	v_pk_mul_f32 v[62:63], v[52:53], v[242:243] op_sel:[1,0] op_sel_hi:[1,1]
	v_add_f32_dpp v58, v58, v58 quad_perm:[1,0,3,2] row_mask:0xf bank_mask:0xf bound_ctrl:1
	v_pk_fma_f32 v[60:61], v[4:5], v[224:225], v[60:61]
	v_add_f32_e32 v66, v64, v65
	v_add_f32_dpp v58, v58, v58 quad_perm:[2,3,0,1] row_mask:0xf bank_mask:0xf bound_ctrl:1
	v_pk_fma_f32 v[62:63], v[6:7], v[226:227], v[62:63]
	v_add_f32_dpp v68, v68, v68 row_half_mirror row_mask:0xf bank_mask:0x5
	v_add_f32_dpp v58, v58, v58 row_half_mirror row_mask:0xf bank_mask:0xf bound_ctrl:1
	s_nop 0
	v_add_f32_dpp v68, v69, v69 row_half_mirror row_mask:0xf bank_mask:0xa
	ds_read_b128 v[40:43], v76 offset:14080
	v_add_f32_dpp v58, v58, v58 row_mirror row_mask:0xf bank_mask:0xf bound_ctrl:1
	v_pk_fma_f32 v[4:5], v[58:59], v[232:233], v[60:61] op_sel_hi:[0,1,1]
	v_pk_fma_f32 v[6:7], v[58:59], v[234:235], v[62:63] op_sel_hi:[0,1,1]
	s_waitcnt lgkmcnt(7)
	ds_read_b128 v[228:231], v76 offset:6144
	ds_read_b128 v[240:243], v76 offset:18432
	ds_read_b128 v[224:227], v76 offset:2048
	ds_read_b128 v[232:235], v76 offset:10240
	v_pk_mul_f32 v[56:57], v[4:5], v[12:13]
	v_pk_mul_f32 v[64:65], v[4:5], v[236:237]
	v_pk_fma_f32 v[56:57], v[6:7], v[14:15], v[56:57]
	v_pk_fma_f32 v[64:65], v[6:7], v[238:239], v[64:65]
	v_add_f32_e32 v58, v56, v57
	v_pk_mul_f32 v[60:61], v[54:55], v[24:25] op_sel_hi:[0,1]
	v_pk_mul_f32 v[62:63], v[54:55], v[26:27] op_sel_hi:[0,1]
	v_add_f32_dpp v58, v58, v58 quad_perm:[1,0,3,2] row_mask:0xf bank_mask:0xf bound_ctrl:1
	v_pk_fma_f32 v[60:61], v[4:5], v[8:9], v[60:61]
	v_add_f32_e32 v67, v64, v65
	v_add_f32_dpp v58, v58, v58 quad_perm:[2,3,0,1] row_mask:0xf bank_mask:0xf bound_ctrl:1
	v_pk_fma_f32 v[62:63], v[6:7], v[10:11], v[62:63]
	v_add_f32_dpp v70, v66, v66 row_mirror row_mask:0xf bank_mask:0x3
	v_add_f32_dpp v58, v58, v58 row_half_mirror row_mask:0xf bank_mask:0xf bound_ctrl:1
	s_nop 0
	v_add_f32_dpp v70, v67, v67 row_mirror row_mask:0xf bank_mask:0xc
	ds_read_b128 v[236:239], v76 offset:14336
	v_add_f32_dpp v58, v58, v58 row_mirror row_mask:0xf bank_mask:0xf bound_ctrl:1
	v_pk_fma_f32 v[4:5], v[58:59], v[16:17], v[60:61] op_sel_hi:[0,1,1]
	v_pk_fma_f32 v[6:7], v[58:59], v[18:19], v[62:63] op_sel_hi:[0,1,1]
	s_waitcnt lgkmcnt(7)
	ds_read_b128 v[12:15], v76 offset:6400
	ds_read_b128 v[24:27], v76 offset:18688
	ds_read_b128 v[8:11], v76 offset:2304
	ds_read_b128 v[16:19], v76 offset:10496
	v_pk_mul_f32 v[56:57], v[4:5], v[32:33]
	v_pk_mul_f32 v[64:65], v[4:5], v[20:21]
	v_pk_fma_f32 v[56:57], v[6:7], v[34:35], v[56:57]
	v_pk_fma_f32 v[64:65], v[6:7], v[22:23], v[64:65]
	v_add_f32_e32 v58, v56, v57
	v_pk_mul_f32 v[60:61], v[54:55], v[44:45] op_sel:[1,0] op_sel_hi:[1,1]
	v_pk_mul_f32 v[62:63], v[54:55], v[46:47] op_sel:[1,0] op_sel_hi:[1,1]
	v_add_f32_dpp v58, v58, v58 quad_perm:[1,0,3,2] row_mask:0xf bank_mask:0xf bound_ctrl:1
	v_pk_fma_f32 v[60:61], v[4:5], v[28:29], v[60:61]
	v_add_f32_e32 v66, v64, v65
	v_add_f32_dpp v58, v58, v58 quad_perm:[2,3,0,1] row_mask:0xf bank_mask:0xf bound_ctrl:1
	v_pk_fma_f32 v[62:63], v[6:7], v[30:31], v[62:63]
	s_nop 0
	v_add_f32_dpp v58, v58, v58 row_half_mirror row_mask:0xf bank_mask:0xf bound_ctrl:1
	ds_read_b128 v[20:23], v76 offset:14592
	s_nop 0
	v_add_f32_dpp v58, v58, v58 row_mirror row_mask:0xf bank_mask:0xf bound_ctrl:1
	v_pk_fma_f32 v[4:5], v[58:59], v[36:37], v[60:61] op_sel_hi:[0,1,1]
	v_pk_fma_f32 v[6:7], v[58:59], v[38:39], v[62:63] op_sel_hi:[0,1,1]
	s_waitcnt lgkmcnt(6)
	ds_read_b128 v[32:35], v76 offset:6656
	ds_read_b128 v[44:47], v76 offset:18944
	ds_read_b128 v[28:31], v76 offset:2560
	ds_read_b128 v[36:39], v76 offset:10752
	v_pk_mul_f32 v[56:57], v[4:5], v[228:229]
	v_pk_mul_f32 v[64:65], v[4:5], v[40:41]
	v_pk_fma_f32 v[56:57], v[6:7], v[230:231], v[56:57]
	v_pk_fma_f32 v[64:65], v[6:7], v[42:43], v[64:65]
	v_add_f32_e32 v58, v56, v57
	v_pk_mul_f32 v[60:61], v[48:49], v[240:241] op_sel_hi:[0,1]
	v_pk_mul_f32 v[62:63], v[48:49], v[242:243] op_sel_hi:[0,1]
	v_add_f32_dpp v58, v58, v58 quad_perm:[1,0,3,2] row_mask:0xf bank_mask:0xf bound_ctrl:1
	v_pk_fma_f32 v[60:61], v[4:5], v[224:225], v[60:61]
	v_add_f32_e32 v67, v64, v65
	v_add_f32_dpp v58, v58, v58 quad_perm:[2,3,0,1] row_mask:0xf bank_mask:0xf bound_ctrl:1
	v_pk_fma_f32 v[62:63], v[6:7], v[226:227], v[62:63]
	v_add_f32_dpp v71, v66, v66 row_mirror row_mask:0xf bank_mask:0x3
	v_add_f32_dpp v58, v58, v58 row_half_mirror row_mask:0xf bank_mask:0xf bound_ctrl:1
	s_nop 0
	v_add_f32_dpp v71, v67, v67 row_mirror row_mask:0xf bank_mask:0xc
	ds_read_b128 v[40:43], v76 offset:14848
	v_add_f32_dpp v58, v58, v58 row_mirror row_mask:0xf bank_mask:0xf bound_ctrl:1
	v_pk_fma_f32 v[4:5], v[58:59], v[232:233], v[60:61] op_sel_hi:[0,1,1]
	v_pk_fma_f32 v[6:7], v[58:59], v[234:235], v[62:63] op_sel_hi:[0,1,1]
	s_waitcnt lgkmcnt(6)
; DI void scan_task(const Params& p, int l, int isP, int b, int h, int rg, char* smem, const bool dry) {
;     ...
;     for (int s = 0; s < 32; s++) {
;       f32x4 w4n = w4, a4n = a4, b4n = b4;
;       uint2 urn = ur, ukn = uk;
;       float vn = v;
;       if (s < 31) {
;         w4n = *(const f32x4*)(fw + (s + 1) * 64);
;         a4n = *(const f32x4*)(fa + (s + 1) * 64);
;         b4n = *(const f32x4*)(fb + (s + 1) * 64);
;         urn = *(const uint2*)(pr + (s + 1) * 128);
;         ukn = *(const uint2*)(pk + (s + 1) * 128);
;         vn = vb[(s + 1) * 16];
;       }
;       __builtin_amdgcn_sched_barrier(0);
;       const f32x2 klo = {__uint_as_float(uk.x << 16), __uint_as_float(uk.x & 0xFFFF0000u)};
;       const f32x2 khi = {__uint_as_float(uk.y << 16), __uint_as_float(uk.y & 0xFFFF0000u)};
;       const f32x2 rlo = {__uint_as_float(ur.x << 16), __uint_as_float(ur.x & 0xFFFF0000u)};
;       const f32x2 rhi = {__uint_as_float(ur.y << 16), __uint_as_float(ur.y & 0xFFFF0000u)};
;       const f32x2 vv = {v, v};
;       const f32x2 t = Sa * a4.lo + Sb * a4.hi;
;       const f32x2 na = Sa * w4.lo + vv * klo;
;       const f32x2 nb = Sb * w4.hi + vv * khi;
;       float sa = t.x + t.y;
;       float yp = yprev;
;       rowsum16x2(sa, yp);
;       if (s >= 1 && s <= 16) ykeep0 = (jq == s - 1) ? yp : ykeep0;
;       if (s >= 17) ykeep1 = (jq == s - 17) ? yp : ykeep1;
;       const f32x2 sv = {sa, sa};
;       Sa = na + sv * b4.lo;
;       Sb = nb + sv * b4.hi;
;       const f32x2 yy = Sa * rlo + Sb * rhi;
;       yprev = yy.x + yy.y;
;       w4 = w4n; a4 = a4n; b4 = b4n; ur = urn; uk = ukn; v = vn;
;     }
	ds_read_b128 v[228:231], v76 offset:6912
	ds_read_b128 v[240:243], v76 offset:19200
	ds_read_b128 v[224:227], v76 offset:2816
	ds_read_b128 v[232:235], v76 offset:11008
	ds_read_b128 v[52:55], v77 offset:20528
	v_pk_mul_f32 v[56:57], v[4:5], v[12:13]
	v_pk_mul_f32 v[64:65], v[4:5], v[236:237]
	v_pk_fma_f32 v[56:57], v[6:7], v[14:15], v[56:57]
	v_pk_fma_f32 v[64:65], v[6:7], v[238:239], v[64:65]
	v_add_f32_e32 v58, v56, v57
	v_pk_mul_f32 v[60:61], v[48:49], v[24:25] op_sel:[1,0] op_sel_hi:[1,1]
	v_pk_mul_f32 v[62:63], v[48:49], v[26:27] op_sel:[1,0] op_sel_hi:[1,1]
	v_add_f32_dpp v58, v58, v58 quad_perm:[1,0,3,2] row_mask:0xf bank_mask:0xf bound_ctrl:1
	v_pk_fma_f32 v[60:61], v[4:5], v[8:9], v[60:61]
	v_add_f32_e32 v66, v64, v65
	v_add_f32_dpp v58, v58, v58 quad_perm:[2,3,0,1] row_mask:0xf bank_mask:0xf bound_ctrl:1
	v_pk_fma_f32 v[62:63], v[6:7], v[10:11], v[62:63]
	v_add_f32_dpp v70, v70, v70 row_half_mirror row_mask:0xf bank_mask:0x5
	v_add_f32_dpp v58, v58, v58 row_half_mirror row_mask:0xf bank_mask:0xf bound_ctrl:1
	s_nop 0
	v_add_f32_dpp v70, v71, v71 row_half_mirror row_mask:0xf bank_mask:0xa
	ds_read_b128 v[236:239], v76 offset:15104
	v_add_f32_dpp v58, v58, v58 row_mirror row_mask:0xf bank_mask:0xf bound_ctrl:1
	v_pk_fma_f32 v[4:5], v[58:59], v[16:17], v[60:61] op_sel_hi:[0,1,1]
	v_pk_fma_f32 v[6:7], v[58:59], v[18:19], v[62:63] op_sel_hi:[0,1,1]
	s_waitcnt lgkmcnt(7)
	ds_read_b128 v[12:15], v76 offset:7168
	ds_read_b128 v[24:27], v76 offset:19456
	ds_read_b128 v[8:11], v76 offset:3072
	ds_read_b128 v[16:19], v76 offset:11264
	v_pk_mul_f32 v[56:57], v[4:5], v[32:33]
	v_pk_mul_f32 v[64:65], v[4:5], v[20:21]
	v_pk_fma_f32 v[56:57], v[6:7], v[34:35], v[56:57]
	v_pk_fma_f32 v[64:65], v[6:7], v[22:23], v[64:65]
	v_add_f32_e32 v58, v56, v57
	v_pk_mul_f32 v[60:61], v[50:51], v[44:45] op_sel_hi:[0,1]
	v_pk_mul_f32 v[62:63], v[50:51], v[46:47] op_sel_hi:[0,1]
	v_add_f32_dpp v58, v58, v58 quad_perm:[1,0,3,2] row_mask:0xf bank_mask:0xf bound_ctrl:1
	v_pk_fma_f32 v[60:61], v[4:5], v[28:29], v[60:61]
	v_add_f32_e32 v67, v64, v65
	v_add_f32_dpp v58, v58, v58 quad_perm:[2,3,0,1] row_mask:0xf bank_mask:0xf bound_ctrl:1
	v_pk_fma_f32 v[62:63], v[6:7], v[30:31], v[62:63]
	v_add_f32_dpp v72, v66, v66 row_mirror row_mask:0xf bank_mask:0x3
	v_add_f32_dpp v58, v58, v58 row_half_mirror row_mask:0xf bank_mask:0xf bound_ctrl:1
	s_nop 0
	v_add_f32_dpp v72, v67, v67 row_mirror row_mask:0xf bank_mask:0xc
	ds_read_b128 v[20:23], v76 offset:15360
	v_add_f32_dpp v58, v58, v58 row_mirror row_mask:0xf bank_mask:0xf bound_ctrl:1
	v_pk_fma_f32 v[4:5], v[58:59], v[36:37], v[60:61] op_sel_hi:[0,1,1]
	v_pk_fma_f32 v[6:7], v[58:59], v[38:39], v[62:63] op_sel_hi:[0,1,1]
	s_waitcnt lgkmcnt(7)
	ds_read_b128 v[32:35], v76 offset:7424
	ds_read_b128 v[44:47], v76 offset:19712
	ds_read_b128 v[28:31], v76 offset:3328
	ds_read_b128 v[36:39], v76 offset:11520
	v_pk_mul_f32 v[56:57], v[4:5], v[228:229]
	v_pk_mul_f32 v[64:65], v[4:5], v[40:41]
	v_pk_fma_f32 v[56:57], v[6:7], v[230:231], v[56:57]
	v_pk_fma_f32 v[64:65], v[6:7], v[42:43], v[64:65]
	v_add_f32_e32 v58, v56, v57
	v_pk_mul_f32 v[60:61], v[50:51], v[240:241] op_sel:[1,0] op_sel_hi:[1,1]
	v_pk_mul_f32 v[62:63], v[50:51], v[242:243] op_sel:[1,0] op_sel_hi:[1,1]
	v_add_f32_dpp v58, v58, v58 quad_perm:[1,0,3,2] row_mask:0xf bank_mask:0xf bound_ctrl:1
	v_pk_fma_f32 v[60:61], v[4:5], v[224:225], v[60:61]
	v_add_f32_e32 v66, v64, v65
	v_add_f32_dpp v58, v58, v58 quad_perm:[2,3,0,1] row_mask:0xf bank_mask:0xf bound_ctrl:1
	v_pk_fma_f32 v[62:63], v[6:7], v[226:227], v[62:63]
	s_nop 0
	v_add_f32_dpp v58, v58, v58 row_half_mirror row_mask:0xf bank_mask:0xf bound_ctrl:1
	ds_read_b128 v[40:43], v76 offset:15616
	s_nop 0
	v_add_f32_dpp v58, v58, v58 row_mirror row_mask:0xf bank_mask:0xf bound_ctrl:1
	v_pk_fma_f32 v[4:5], v[58:59], v[232:233], v[60:61] op_sel_hi:[0,1,1]
	v_pk_fma_f32 v[6:7], v[58:59], v[234:235], v[62:63] op_sel_hi:[0,1,1]
	s_waitcnt lgkmcnt(6)
; DI void scan_task(const Params& p, int l, int isP, int b, int h, int rg, char* smem, const bool dry) {
;     ...
;     for (int s = 0; s < 32; s++) {
;       f32x4 w4n = w4, a4n = a4, b4n = b4;
;       uint2 urn = ur, ukn = uk;
;       float vn = v;
;       if (s < 31) {
;         w4n = *(const f32x4*)(fw + (s + 1) * 64);
;         a4n = *(const f32x4*)(fa + (s + 1) * 64);
;         b4n = *(const f32x4*)(fb + (s + 1) * 64);
;         urn = *(const uint2*)(pr + (s + 1) * 128);
;         ukn = *(const uint2*)(pk + (s + 1) * 128);
;         vn = vb[(s + 1) * 16];
;       }
;       __builtin_amdgcn_sched_barrier(0);
;       const f32x2 klo = {__uint_as_float(uk.x << 16), __uint_as_float(uk.x & 0xFFFF0000u)};
;       const f32x2 khi = {__uint_as_float(uk.y << 16), __uint_as_float(uk.y & 0xFFFF0000u)};
;       const f32x2 rlo = {__uint_as_float(ur.x << 16), __uint_as_float(ur.x & 0xFFFF0000u)};
;       const f32x2 rhi = {__uint_as_float(ur.y << 16), __uint_as_float(ur.y & 0xFFFF0000u)};
;       const f32x2 vv = {v, v};
;       const f32x2 t = Sa * a4.lo + Sb * a4.hi;
;       const f32x2 na = Sa * w4.lo + vv * klo;
;       const f32x2 nb = Sb * w4.hi + vv * khi;
;       float sa = t.x + t.y;
;       float yp = yprev;
;       rowsum16x2(sa, yp);
;       if (s >= 1 && s <= 16) ykeep0 = (jq == s - 1) ? yp : ykeep0;
;       if (s >= 17) ykeep1 = (jq == s - 17) ? yp : ykeep1;
;       const f32x2 sv = {sa, sa};
;       Sa = na + sv * b4.lo;
;       Sb = nb + sv * b4.hi;
;       const f32x2 yy = Sa * rlo + Sb * rhi;
;       yprev = yy.x + yy.y;
;       w4 = w4n; a4 = a4n; b4 = b4n; ur = urn; uk = ukn; v = vn;
;     }
;     {
;       const float yl = rowsum16(yprev);
;       ykeep1 = (jq == 15) ? yl : ykeep1;
;     }
;     if (!dry) { yo[0] = ykeep0; yo[(size_t)16 * 512] = ykeep1; }
;     if (more) sstore((c + 1) & 1);
	ds_read_b128 v[228:231], v76 offset:7680
	ds_read_b128 v[240:243], v76 offset:19968
	ds_read_b128 v[224:227], v76 offset:3584
	ds_read_b128 v[232:235], v76 offset:11776
	v_pk_mul_f32 v[56:57], v[4:5], v[12:13]
	v_pk_mul_f32 v[64:65], v[4:5], v[236:237]
	v_pk_fma_f32 v[56:57], v[6:7], v[14:15], v[56:57]
	v_pk_fma_f32 v[64:65], v[6:7], v[238:239], v[64:65]
	v_add_f32_e32 v58, v56, v57
	v_pk_mul_f32 v[60:61], v[52:53], v[24:25] op_sel_hi:[0,1]
	v_pk_mul_f32 v[62:63], v[52:53], v[26:27] op_sel_hi:[0,1]
	v_add_f32_dpp v58, v58, v58 quad_perm:[1,0,3,2] row_mask:0xf bank_mask:0xf bound_ctrl:1
	v_pk_fma_f32 v[60:61], v[4:5], v[8:9], v[60:61]
	v_add_f32_e32 v67, v64, v65
	v_add_f32_dpp v58, v58, v58 quad_perm:[2,3,0,1] row_mask:0xf bank_mask:0xf bound_ctrl:1
	v_pk_fma_f32 v[62:63], v[6:7], v[10:11], v[62:63]
	v_add_f32_dpp v73, v66, v66 row_mirror row_mask:0xf bank_mask:0x3
	v_add_f32_dpp v58, v58, v58 row_half_mirror row_mask:0xf bank_mask:0xf bound_ctrl:1
	s_nop 0
	v_add_f32_dpp v73, v67, v67 row_mirror row_mask:0xf bank_mask:0xc
	ds_read_b128 v[236:239], v76 offset:15872
	v_add_f32_dpp v58, v58, v58 row_mirror row_mask:0xf bank_mask:0xf bound_ctrl:1
	v_pk_fma_f32 v[4:5], v[58:59], v[16:17], v[60:61] op_sel_hi:[0,1,1]
	v_pk_fma_f32 v[6:7], v[58:59], v[18:19], v[62:63] op_sel_hi:[0,1,1]
	s_waitcnt lgkmcnt(6)
	ds_read_b128 v[12:15], v76 offset:7936
	ds_read_b128 v[24:27], v76 offset:20224
	ds_read_b128 v[8:11], v76 offset:3840
	ds_read_b128 v[16:19], v76 offset:12032
	v_pk_mul_f32 v[56:57], v[4:5], v[32:33]
	v_pk_mul_f32 v[64:65], v[4:5], v[20:21]
	v_pk_fma_f32 v[56:57], v[6:7], v[34:35], v[56:57]
	v_pk_fma_f32 v[64:65], v[6:7], v[22:23], v[64:65]
	v_add_f32_e32 v58, v56, v57
	v_pk_mul_f32 v[60:61], v[52:53], v[44:45] op_sel:[1,0] op_sel_hi:[1,1]
	v_pk_mul_f32 v[62:63], v[52:53], v[46:47] op_sel:[1,0] op_sel_hi:[1,1]
	v_add_f32_dpp v58, v58, v58 quad_perm:[1,0,3,2] row_mask:0xf bank_mask:0xf bound_ctrl:1
	v_pk_fma_f32 v[60:61], v[4:5], v[28:29], v[60:61]
	v_add_f32_e32 v66, v64, v65
	v_add_f32_dpp v58, v58, v58 quad_perm:[2,3,0,1] row_mask:0xf bank_mask:0xf bound_ctrl:1
	v_pk_fma_f32 v[62:63], v[6:7], v[30:31], v[62:63]
	v_add_f32_dpp v72, v72, v72 row_half_mirror row_mask:0xf bank_mask:0x5
	v_add_f32_dpp v58, v58, v58 row_half_mirror row_mask:0xf bank_mask:0xf bound_ctrl:1
	s_nop 0
	v_add_f32_dpp v72, v73, v73 row_half_mirror row_mask:0xf bank_mask:0xa
	ds_read_b128 v[20:23], v76 offset:16128
	v_add_f32_dpp v58, v58, v58 row_mirror row_mask:0xf bank_mask:0xf bound_ctrl:1
	v_pk_fma_f32 v[4:5], v[58:59], v[36:37], v[60:61] op_sel_hi:[0,1,1]
	v_pk_fma_f32 v[6:7], v[58:59], v[38:39], v[62:63] op_sel_hi:[0,1,1]
	s_waitcnt lgkmcnt(6)
	v_pk_mul_f32 v[56:57], v[4:5], v[228:229]
	v_pk_mul_f32 v[64:65], v[4:5], v[40:41]
	v_pk_fma_f32 v[56:57], v[6:7], v[230:231], v[56:57]
	v_pk_fma_f32 v[64:65], v[6:7], v[42:43], v[64:65]
	v_add_f32_e32 v58, v56, v57
	v_pk_mul_f32 v[60:61], v[54:55], v[240:241] op_sel_hi:[0,1]
	v_pk_mul_f32 v[62:63], v[54:55], v[242:243] op_sel_hi:[0,1]
	v_add_f32_dpp v58, v58, v58 quad_perm:[1,0,3,2] row_mask:0xf bank_mask:0xf bound_ctrl:1
	v_pk_fma_f32 v[60:61], v[4:5], v[224:225], v[60:61]
	v_add_f32_e32 v67, v64, v65
	v_add_f32_dpp v58, v58, v58 quad_perm:[2,3,0,1] row_mask:0xf bank_mask:0xf bound_ctrl:1
	v_pk_fma_f32 v[62:63], v[6:7], v[226:227], v[62:63]
	v_add_f32_dpp v74, v66, v66 row_mirror row_mask:0xf bank_mask:0x3
	v_add_f32_dpp v58, v58, v58 row_half_mirror row_mask:0xf bank_mask:0xf bound_ctrl:1
	s_nop 0
	v_add_f32_dpp v74, v67, v67 row_mirror row_mask:0xf bank_mask:0xc
	v_add_f32_dpp v58, v58, v58 row_mirror row_mask:0xf bank_mask:0xf bound_ctrl:1
	v_pk_fma_f32 v[4:5], v[58:59], v[232:233], v[60:61] op_sel_hi:[0,1,1]
	v_pk_fma_f32 v[6:7], v[58:59], v[234:235], v[62:63] op_sel_hi:[0,1,1]
	s_waitcnt lgkmcnt(1)
	v_pk_mul_f32 v[56:57], v[4:5], v[12:13]
	v_pk_mul_f32 v[64:65], v[4:5], v[236:237]
	v_pk_fma_f32 v[56:57], v[6:7], v[14:15], v[56:57]
	v_pk_fma_f32 v[64:65], v[6:7], v[238:239], v[64:65]
	v_add_f32_e32 v58, v56, v57
	v_pk_mul_f32 v[60:61], v[54:55], v[24:25] op_sel:[1,0] op_sel_hi:[1,1]
	v_pk_mul_f32 v[62:63], v[54:55], v[26:27] op_sel:[1,0] op_sel_hi:[1,1]
	v_add_f32_dpp v58, v58, v58 quad_perm:[1,0,3,2] row_mask:0xf bank_mask:0xf bound_ctrl:1
	v_pk_fma_f32 v[60:61], v[4:5], v[8:9], v[60:61]
	v_add_f32_e32 v66, v64, v65
	v_add_f32_dpp v58, v58, v58 quad_perm:[2,3,0,1] row_mask:0xf bank_mask:0xf bound_ctrl:1
	v_pk_fma_f32 v[62:63], v[6:7], v[10:11], v[62:63]
	s_nop 0
	v_add_f32_dpp v58, v58, v58 row_half_mirror row_mask:0xf bank_mask:0xf bound_ctrl:1
	s_nop 1
	v_add_f32_dpp v58, v58, v58 row_mirror row_mask:0xf bank_mask:0xf bound_ctrl:1
	v_pk_fma_f32 v[4:5], v[58:59], v[16:17], v[60:61] op_sel_hi:[0,1,1]
	v_pk_fma_f32 v[6:7], v[58:59], v[18:19], v[62:63] op_sel_hi:[0,1,1]
	s_waitcnt lgkmcnt(0)
	v_pk_mul_f32 v[64:65], v[4:5], v[20:21]
	v_pk_fma_f32 v[64:65], v[6:7], v[22:23], v[64:65]
	v_add_f32_e32 v67, v64, v65
	s_cmp_lg_u32 s22, 0
	s_cbranch_scc1 .Lscan_w6A
	s_waitcnt vmcnt(0)
	s_branch .Lscan_wdA

; DI void scan_task(const Params& p, int l, int isP, int b, int h, int rg, char* smem, const bool dry) {
;     ...
;   auto gload = [&](int c) {
;     const int tk = tokbase + c * 32;
;     rd0 = *(const float4*)(p.R + (size_t)(tk + ds) * RS + h * 64 + dj * 4);
;     rd1 = *(const float4*)(p.R + (size_t)(tk + 16 + ds) * RS + h * 64 + dj * 4);
;     const bf16_t* rb = (const bf16_t*)(p.R + (size_t)(tk + lst) * RS + 512) + h * 64 + lch * 8;
;     qr = *(const uint4*)(rb);
;     qk = *(const uint4*)(rb + 512);
;     qa = *(const uint4*)(rb + 1536);
;     qb = *(const uint4*)(rb + 2048);
;     if (tid < 64) {
;       const int s = tid >> 1, half = tid & 1;
;       rv = *(const uint4*)((const bf16_t*)(p.R + (size_t)(tk + s) * RS + 512) + 1024 + h * 64 + rg * 16 + half * 8);
;     }
;   };
;     ...
;   auto sstore = [&](int bi) {
;     char* bb = smem + bi * BUFB;
;     *(float4*)(bb + (ds * 64 + dj * 4) * 4) = rd0;
;     *(float4*)(bb + ((16 + ds) * 64 + dj * 4) * 4) = rd1;
;     {
;       CVT8(qa, alo, ahi)
;       float* d = (float*)(bb + 8192) + lst * 64 + lch * 8;
;       *(float4*)d = alo; *(float4*)(d + 4) = ahi;
;     }
;     {
;       CVT8(qb, blo, bhi)
;       float* d = (float*)(bb + 16384) + lst * 64 + lch * 8;
;       *(float4*)d = blo; *(float4*)(d + 4) = bhi;
;     }
;     *(uint4*)(bb + 24576 + (lst * 64 + lch * 8) * 2) = qr;
;     *(uint4*)(bb + 28672 + (lst * 64 + lch * 8) * 2) = qk;
;     if (tid < 64) {
;       const int s = tid >> 1, half = tid & 1;
;       CVT8(rv, vlo, vhi)
;       float* d = (float*)(bb + 32768) + s * 16 + half * 8;
;       *(float4*)d = vlo; *(float4*)(d + 4) = vhi;
;     }
;   };
.Lscan_wdA:
	ds_write_b128 v78, v[100:103] offset:21504
	v_lshlrev_b32_e32 v8, 16, v108
	v_and_b32_e32 v9, 0xffff0000, v108
	v_lshlrev_b32_e32 v10, 16, v109
	v_and_b32_e32 v11, 0xffff0000, v109
	ds_write_b128 v78, v[8:11] offset:25600
	v_lshlrev_b32_e32 v12, 16, v98
	v_and_b32_e32 v13, 0xffff0000, v98
	v_lshlrev_b32_e32 v14, 16, v99
	v_and_b32_e32 v15, 0xffff0000, v99
	ds_write_b128 v78, v[12:15] offset:29696
	v_lshlrev_b32_e32 v16, 16, v104
	v_and_b32_e32 v17, 0xffff0000, v104
	v_lshlrev_b32_e32 v18, 16, v105
	v_and_b32_e32 v19, 0xffff0000, v105
	ds_write_b128 v78, v[16:19] offset:33792
	v_lshlrev_b32_e32 v20, 16, v106
	v_and_b32_e32 v21, 0xffff0000, v106
	v_lshlrev_b32_e32 v22, 16, v107
	v_and_b32_e32 v23, 0xffff0000, v107
	ds_write_b128 v78, v[20:23] offset:37888
	v_lshlrev_b32_e32 v24, 16, v97
	ds_write_b32 v79, v24 offset:41984
	s_add_i32 s23, s16, 3
	s_cmp_lt_u32 s23, s17
	s_cselect_b32 s22, 1, 0
	s_cbranch_scc0 .Lscan_noldA
	global_load_dwordx4 v[100:103], v80, s[12:13]
	global_load_dwordx2 v[104:105], v81, s[12:13] offset:-1024
	global_load_dwordx2 v[106:107], v81, s[12:13]
	global_load_dwordx2 v[108:109], v81, s[12:13] offset:2048
	global_load_dwordx2 v[98:99], v81, s[12:13] offset:3072
	global_load_ushort v97, v82, s[12:13]
	s_add_u32 s12, s12, 0x1c000
	s_addc_u32 s13, s13, 0
.Lscan_noldA:
	s_waitcnt lgkmcnt(0)
	s_barrier
	s_cmp_eq_u32 s28, 0
	s_cbranch_scc1 .LstgbA
	s_nop 5
	s_cmp_eq_u32 s28, 1
	s_cbranch_scc1 .LstgbA
	s_nop 5
	s_cmp_eq_u32 s28, 2
	s_cbranch_scc1 .LstgbA
	s_nop 5

; DI void scan_task(const Params& p, int l, int isP, int b, int h, int rg, char* smem, const bool dry) {
;     ...
;     for (int s = 0; s < 32; s++) {
;       f32x4 w4n = w4, a4n = a4, b4n = b4;
;       uint2 urn = ur, ukn = uk;
;       float vn = v;
;       if (s < 31) {
;         w4n = *(const f32x4*)(fw + (s + 1) * 64);
;         a4n = *(const f32x4*)(fa + (s + 1) * 64);
;         b4n = *(const f32x4*)(fb + (s + 1) * 64);
;         urn = *(const uint2*)(pr + (s + 1) * 128);
;         ukn = *(const uint2*)(pk + (s + 1) * 128);
;         vn = vb[(s + 1) * 16];
;       }
;       __builtin_amdgcn_sched_barrier(0);
;       const f32x2 klo = {__uint_as_float(uk.x << 16), __uint_as_float(uk.x & 0xFFFF0000u)};
;       const f32x2 khi = {__uint_as_float(uk.y << 16), __uint_as_float(uk.y & 0xFFFF0000u)};
;       const f32x2 rlo = {__uint_as_float(ur.x << 16), __uint_as_float(ur.x & 0xFFFF0000u)};
;       const f32x2 rhi = {__uint_as_float(ur.y << 16), __uint_as_float(ur.y & 0xFFFF0000u)};
;       const f32x2 vv = {v, v};
;       const f32x2 t = Sa * a4.lo + Sb * a4.hi;
;       const f32x2 na = Sa * w4.lo + vv * klo;
;       const f32x2 nb = Sb * w4.hi + vv * khi;
;       float sa = t.x + t.y;
;       float yp = yprev;
;       rowsum16x2(sa, yp);
;       if (s >= 1 && s <= 16) ykeep0 = (jq == s - 1) ? yp : ykeep0;
;       if (s >= 17) ykeep1 = (jq == s - 17) ? yp : ykeep1;
;       const f32x2 sv = {sa, sa};
;       Sa = na + sv * b4.lo;
;       Sb = nb + sv * b4.hi;
;       const f32x2 yy = Sa * rlo + Sb * rhi;
;       yprev = yy.x + yy.y;
;       w4 = w4n; a4 = a4n; b4 = b4n; ur = urn; uk = ukn; v = vn;
;     }
.Lscan_bodyB:
	s_waitcnt lgkmcnt(6)
	ds_read_b128 v[228:231], v76 offset:26112
	ds_read_b128 v[240:243], v76 offset:38400
	ds_read_b128 v[224:227], v76 offset:22016
	ds_read_b128 v[232:235], v76 offset:30208
	ds_read_b128 v[236:239], v76 offset:34304
	v_pk_mul_f32 v[56:57], v[4:5], v[12:13]
	v_pk_fma_f32 v[56:57], v[6:7], v[14:15], v[56:57]
	v_add_f32_e32 v58, v56, v57
	v_pk_mul_f32 v[60:61], v[48:49], v[24:25] op_sel_hi:[0,1]
	v_pk_mul_f32 v[62:63], v[48:49], v[26:27] op_sel_hi:[0,1]
	v_add_f32_dpp v58, v58, v58 quad_perm:[1,0,3,2] row_mask:0xf bank_mask:0xf bound_ctrl:1
	v_pk_fma_f32 v[60:61], v[4:5], v[8:9], v[60:61]
	v_pk_fma_f32 v[62:63], v[6:7], v[10:11], v[62:63]
	v_add_f32_dpp v58, v58, v58 quad_perm:[2,3,0,1] row_mask:0xf bank_mask:0xf bound_ctrl:1
	s_nop 1
	v_add_f32_dpp v58, v58, v58 row_half_mirror row_mask:0xf bank_mask:0xf bound_ctrl:1
	s_nop 1
	v_add_f32_dpp v58, v58, v58 row_mirror row_mask:0xf bank_mask:0xf bound_ctrl:1
	v_pk_fma_f32 v[4:5], v[58:59], v[16:17], v[60:61] op_sel_hi:[0,1,1]
	v_pk_fma_f32 v[6:7], v[58:59], v[18:19], v[62:63] op_sel_hi:[0,1,1]
	s_waitcnt lgkmcnt(6)
	ds_read_b128 v[12:15], v76 offset:26368
	ds_read_b128 v[24:27], v76 offset:38656
	ds_read_b128 v[8:11], v76 offset:22272
	ds_read_b128 v[16:19], v76 offset:30464
	ds_read_b128 v[52:55], v77 offset:42000
	v_pk_mul_f32 v[56:57], v[4:5], v[32:33]
	v_pk_mul_f32 v[64:65], v[4:5], v[20:21]
	v_pk_fma_f32 v[56:57], v[6:7], v[34:35], v[56:57]
	v_pk_fma_f32 v[64:65], v[6:7], v[22:23], v[64:65]
	v_add_f32_e32 v58, v56, v57
	v_pk_mul_f32 v[60:61], v[48:49], v[44:45] op_sel:[1,0] op_sel_hi:[1,1]
	v_pk_mul_f32 v[62:63], v[48:49], v[46:47] op_sel:[1,0] op_sel_hi:[1,1]
	v_add_f32_dpp v58, v58, v58 quad_perm:[1,0,3,2] row_mask:0xf bank_mask:0xf bound_ctrl:1
	v_pk_fma_f32 v[60:61], v[4:5], v[28:29], v[60:61]
	v_add_f32_e32 v66, v64, v65
	v_add_f32_dpp v58, v58, v58 quad_perm:[2,3,0,1] row_mask:0xf bank_mask:0xf bound_ctrl:1
	v_pk_fma_f32 v[62:63], v[6:7], v[30:31], v[62:63]
	s_nop 0
	v_add_f32_dpp v58, v58, v58 row_half_mirror row_mask:0xf bank_mask:0xf bound_ctrl:1
	ds_read_b128 v[20:23], v76 offset:34560
	s_nop 0
	v_add_f32_dpp v58, v58, v58 row_mirror row_mask:0xf bank_mask:0xf bound_ctrl:1
	v_pk_fma_f32 v[4:5], v[58:59], v[36:37], v[60:61] op_sel_hi:[0,1,1]
	v_pk_fma_f32 v[6:7], v[58:59], v[38:39], v[62:63] op_sel_hi:[0,1,1]
	s_waitcnt lgkmcnt(7)
	ds_read_b128 v[32:35], v76 offset:26624
	ds_read_b128 v[44:47], v76 offset:38912
	ds_read_b128 v[28:31], v76 offset:22528
	ds_read_b128 v[36:39], v76 offset:30720
	v_pk_mul_f32 v[56:57], v[4:5], v[228:229]
	v_pk_mul_f32 v[64:65], v[4:5], v[40:41]
	v_pk_fma_f32 v[56:57], v[6:7], v[230:231], v[56:57]
	v_pk_fma_f32 v[64:65], v[6:7], v[42:43], v[64:65]
	v_add_f32_e32 v58, v56, v57
	v_pk_mul_f32 v[60:61], v[50:51], v[240:241] op_sel_hi:[0,1]
	v_pk_mul_f32 v[62:63], v[50:51], v[242:243] op_sel_hi:[0,1]
	v_add_f32_dpp v58, v58, v58 quad_perm:[1,0,3,2] row_mask:0xf bank_mask:0xf bound_ctrl:1
	v_pk_fma_f32 v[60:61], v[4:5], v[224:225], v[60:61]
	v_add_f32_e32 v67, v64, v65
	v_add_f32_dpp v58, v58, v58 quad_perm:[2,3,0,1] row_mask:0xf bank_mask:0xf bound_ctrl:1
	v_pk_fma_f32 v[62:63], v[6:7], v[226:227], v[62:63]
	v_add_f32_dpp v68, v66, v66 row_mirror row_mask:0xf bank_mask:0x3
	v_add_f32_dpp v58, v58, v58 row_half_mirror row_mask:0xf bank_mask:0xf bound_ctrl:1
	s_nop 0
	v_add_f32_dpp v68, v67, v67 row_mirror row_mask:0xf bank_mask:0xc
	ds_read_b128 v[40:43], v76 offset:34816
	v_add_f32_dpp v58, v58, v58 row_mirror row_mask:0xf bank_mask:0xf bound_ctrl:1
	v_pk_fma_f32 v[4:5], v[58:59], v[232:233], v[60:61] op_sel_hi:[0,1,1]
	v_pk_fma_f32 v[6:7], v[58:59], v[234:235], v[62:63] op_sel_hi:[0,1,1]
	s_waitcnt lgkmcnt(7)
	ds_read_b128 v[228:231], v76 offset:26880
	ds_read_b128 v[240:243], v76 offset:39168
	ds_read_b128 v[224:227], v76 offset:22784
	ds_read_b128 v[232:235], v76 offset:30976
	v_pk_mul_f32 v[56:57], v[4:5], v[12:13]
	v_pk_mul_f32 v[64:65], v[4:5], v[236:237]
	v_pk_fma_f32 v[56:57], v[6:7], v[14:15], v[56:57]
	v_pk_fma_f32 v[64:65], v[6:7], v[238:239], v[64:65]
	v_add_f32_e32 v58, v56, v57
	v_pk_mul_f32 v[60:61], v[50:51], v[24:25] op_sel:[1,0] op_sel_hi:[1,1]
	v_pk_mul_f32 v[62:63], v[50:51], v[26:27] op_sel:[1,0] op_sel_hi:[1,1]
	v_add_f32_dpp v58, v58, v58 quad_perm:[1,0,3,2] row_mask:0xf bank_mask:0xf bound_ctrl:1
	v_pk_fma_f32 v[60:61], v[4:5], v[8:9], v[60:61]
	v_add_f32_e32 v66, v64, v65
	v_add_f32_dpp v58, v58, v58 quad_perm:[2,3,0,1] row_mask:0xf bank_mask:0xf bound_ctrl:1
	v_pk_fma_f32 v[62:63], v[6:7], v[10:11], v[62:63]
	s_nop 0
	v_add_f32_dpp v58, v58, v58 row_half_mirror row_mask:0xf bank_mask:0xf bound_ctrl:1
	ds_read_b128 v[236:239], v76 offset:35072
	s_nop 0
	v_add_f32_dpp v58, v58, v58 row_mirror row_mask:0xf bank_mask:0xf bound_ctrl:1
	v_pk_fma_f32 v[4:5], v[58:59], v[16:17], v[60:61] op_sel_hi:[0,1,1]
	v_pk_fma_f32 v[6:7], v[58:59], v[18:19], v[62:63] op_sel_hi:[0,1,1]
	s_waitcnt lgkmcnt(6)
	ds_read_b128 v[12:15], v76 offset:27136
	ds_read_b128 v[24:27], v76 offset:39424
	ds_read_b128 v[8:11], v76 offset:23040
	ds_read_b128 v[16:19], v76 offset:31232
	v_pk_mul_f32 v[56:57], v[4:5], v[32:33]
	v_pk_mul_f32 v[64:65], v[4:5], v[20:21]
	v_pk_fma_f32 v[56:57], v[6:7], v[34:35], v[56:57]
	v_pk_fma_f32 v[64:65], v[6:7], v[22:23], v[64:65]
	v_add_f32_e32 v58, v56, v57
	v_pk_mul_f32 v[60:61], v[52:53], v[44:45] op_sel_hi:[0,1]
	v_pk_mul_f32 v[62:63], v[52:53], v[46:47] op_sel_hi:[0,1]
	v_add_f32_dpp v58, v58, v58 quad_perm:[1,0,3,2] row_mask:0xf bank_mask:0xf bound_ctrl:1
	v_pk_fma_f32 v[60:61], v[4:5], v[28:29], v[60:61]
	v_add_f32_e32 v67, v64, v65
	v_add_f32_dpp v58, v58, v58 quad_perm:[2,3,0,1] row_mask:0xf bank_mask:0xf bound_ctrl:1
	v_pk_fma_f32 v[62:63], v[6:7], v[30:31], v[62:63]
	v_add_f32_dpp v69, v66, v66 row_mirror row_mask:0xf bank_mask:0x3
	v_add_f32_dpp v58, v58, v58 row_half_mirror row_mask:0xf bank_mask:0xf bound_ctrl:1
	s_nop 0
	v_add_f32_dpp v69, v67, v67 row_mirror row_mask:0xf bank_mask:0xc
	ds_read_b128 v[20:23], v76 offset:35328
	v_add_f32_dpp v58, v58, v58 row_mirror row_mask:0xf bank_mask:0xf bound_ctrl:1
	v_pk_fma_f32 v[4:5], v[58:59], v[36:37], v[60:61] op_sel_hi:[0,1,1]
	v_pk_fma_f32 v[6:7], v[58:59], v[38:39], v[62:63] op_sel_hi:[0,1,1]
	s_waitcnt lgkmcnt(6)
; DI void scan_task(const Params& p, int l, int isP, int b, int h, int rg, char* smem, const bool dry) {
;     ...
;     for (int s = 0; s < 32; s++) {
;       f32x4 w4n = w4, a4n = a4, b4n = b4;
;       uint2 urn = ur, ukn = uk;
;       float vn = v;
;       if (s < 31) {
;         w4n = *(const f32x4*)(fw + (s + 1) * 64);
;         a4n = *(const f32x4*)(fa + (s + 1) * 64);
;         b4n = *(const f32x4*)(fb + (s + 1) * 64);
;         urn = *(const uint2*)(pr + (s + 1) * 128);
;         ukn = *(const uint2*)(pk + (s + 1) * 128);
;         vn = vb[(s + 1) * 16];
;       }
;       __builtin_amdgcn_sched_barrier(0);
;       const f32x2 klo = {__uint_as_float(uk.x << 16), __uint_as_float(uk.x & 0xFFFF0000u)};
;       const f32x2 khi = {__uint_as_float(uk.y << 16), __uint_as_float(uk.y & 0xFFFF0000u)};
;       const f32x2 rlo = {__uint_as_float(ur.x << 16), __uint_as_float(ur.x & 0xFFFF0000u)};
;       const f32x2 rhi = {__uint_as_float(ur.y << 16), __uint_as_float(ur.y & 0xFFFF0000u)};
;       const f32x2 vv = {v, v};
;       const f32x2 t = Sa * a4.lo + Sb * a4.hi;
;       const f32x2 na = Sa * w4.lo + vv * klo;
;       const f32x2 nb = Sb * w4.hi + vv * khi;
;       float sa = t.x + t.y;
;       float yp = yprev;
;       rowsum16x2(sa, yp);
;       if (s >= 1 && s <= 16) ykeep0 = (jq == s - 1) ? yp : ykeep0;
;       if (s >= 17) ykeep1 = (jq == s - 17) ? yp : ykeep1;
;       const f32x2 sv = {sa, sa};
;       Sa = na + sv * b4.lo;
;       Sb = nb + sv * b4.hi;
;       const f32x2 yy = Sa * rlo + Sb * rhi;
;       yprev = yy.x + yy.y;
;       w4 = w4n; a4 = a4n; b4 = b4n; ur = urn; uk = ukn; v = vn;
;     }
	ds_read_b128 v[32:35], v76 offset:27392
	ds_read_b128 v[44:47], v76 offset:39680
	ds_read_b128 v[28:31], v76 offset:23296
	ds_read_b128 v[36:39], v76 offset:31488
	ds_read_b128 v[48:51], v77 offset:42016
	v_pk_mul_f32 v[56:57], v[4:5], v[228:229]
	v_pk_mul_f32 v[64:65], v[4:5], v[40:41]
	v_pk_fma_f32 v[56:57], v[6:7], v[230:231], v[56:57]
	v_pk_fma_f32 v[64:65], v[6:7], v[42:43], v[64:65]
	v_add_f32_e32 v58, v56, v57
	v_pk_mul_f32 v[60:61], v[52:53], v[240:241] op_sel:[1,0] op_sel_hi:[1,1]
	v_pk_mul_f32 v[62:63], v[52:53], v[242:243] op_sel:[1,0] op_sel_hi:[1,1]
	v_add_f32_dpp v58, v58, v58 quad_perm:[1,0,3,2] row_mask:0xf bank_mask:0xf bound_ctrl:1
	v_pk_fma_f32 v[60:61], v[4:5], v[224:225], v[60:61]
	v_add_f32_e32 v66, v64, v65
	v_add_f32_dpp v58, v58, v58 quad_perm:[2,3,0,1] row_mask:0xf bank_mask:0xf bound_ctrl:1
	v_pk_fma_f32 v[62:63], v[6:7], v[226:227], v[62:63]
	v_add_f32_dpp v68, v68, v68 row_half_mirror row_mask:0xf bank_mask:0x5
	v_add_f32_dpp v58, v58, v58 row_half_mirror row_mask:0xf bank_mask:0xf bound_ctrl:1
	s_nop 0
	v_add_f32_dpp v68, v69, v69 row_half_mirror row_mask:0xf bank_mask:0xa
	ds_read_b128 v[40:43], v76 offset:35584
	v_add_f32_dpp v58, v58, v58 row_mirror row_mask:0xf bank_mask:0xf bound_ctrl:1
	v_pk_fma_f32 v[4:5], v[58:59], v[232:233], v[60:61] op_sel_hi:[0,1,1]
	v_pk_fma_f32 v[6:7], v[58:59], v[234:235], v[62:63] op_sel_hi:[0,1,1]
	s_waitcnt lgkmcnt(7)
	ds_read_b128 v[228:231], v76 offset:27648
	ds_read_b128 v[240:243], v76 offset:39936
	ds_read_b128 v[224:227], v76 offset:23552
	ds_read_b128 v[232:235], v76 offset:31744
	v_pk_mul_f32 v[56:57], v[4:5], v[12:13]
	v_pk_mul_f32 v[64:65], v[4:5], v[236:237]
	v_pk_fma_f32 v[56:57], v[6:7], v[14:15], v[56:57]
	v_pk_fma_f32 v[64:65], v[6:7], v[238:239], v[64:65]
	v_add_f32_e32 v58, v56, v57
	v_pk_mul_f32 v[60:61], v[54:55], v[24:25] op_sel_hi:[0,1]
	v_pk_mul_f32 v[62:63], v[54:55], v[26:27] op_sel_hi:[0,1]
	v_add_f32_dpp v58, v58, v58 quad_perm:[1,0,3,2] row_mask:0xf bank_mask:0xf bound_ctrl:1
	v_pk_fma_f32 v[60:61], v[4:5], v[8:9], v[60:61]
	v_add_f32_e32 v67, v64, v65
	v_add_f32_dpp v58, v58, v58 quad_perm:[2,3,0,1] row_mask:0xf bank_mask:0xf bound_ctrl:1
	v_pk_fma_f32 v[62:63], v[6:7], v[10:11], v[62:63]
	v_add_f32_dpp v70, v66, v66 row_mirror row_mask:0xf bank_mask:0x3
	v_add_f32_dpp v58, v58, v58 row_half_mirror row_mask:0xf bank_mask:0xf bound_ctrl:1
	s_nop 0
	v_add_f32_dpp v70, v67, v67 row_mirror row_mask:0xf bank_mask:0xc
	ds_read_b128 v[236:239], v76 offset:35840
	v_add_f32_dpp v58, v58, v58 row_mirror row_mask:0xf bank_mask:0xf bound_ctrl:1
	v_pk_fma_f32 v[4:5], v[58:59], v[16:17], v[60:61] op_sel_hi:[0,1,1]
	v_pk_fma_f32 v[6:7], v[58:59], v[18:19], v[62:63] op_sel_hi:[0,1,1]
	s_waitcnt lgkmcnt(7)
	ds_read_b128 v[12:15], v76 offset:27904
	ds_read_b128 v[24:27], v76 offset:40192
	ds_read_b128 v[8:11], v76 offset:23808
	ds_read_b128 v[16:19], v76 offset:32000
	v_pk_mul_f32 v[56:57], v[4:5], v[32:33]
	v_pk_mul_f32 v[64:65], v[4:5], v[20:21]
	v_pk_fma_f32 v[56:57], v[6:7], v[34:35], v[56:57]
	v_pk_fma_f32 v[64:65], v[6:7], v[22:23], v[64:65]
	v_add_f32_e32 v58, v56, v57
	v_pk_mul_f32 v[60:61], v[54:55], v[44:45] op_sel:[1,0] op_sel_hi:[1,1]
	v_pk_mul_f32 v[62:63], v[54:55], v[46:47] op_sel:[1,0] op_sel_hi:[1,1]
	v_add_f32_dpp v58, v58, v58 quad_perm:[1,0,3,2] row_mask:0xf bank_mask:0xf bound_ctrl:1
	v_pk_fma_f32 v[60:61], v[4:5], v[28:29], v[60:61]
	v_add_f32_e32 v66, v64, v65
	v_add_f32_dpp v58, v58, v58 quad_perm:[2,3,0,1] row_mask:0xf bank_mask:0xf bound_ctrl:1
	v_pk_fma_f32 v[62:63], v[6:7], v[30:31], v[62:63]
	s_nop 0
	v_add_f32_dpp v58, v58, v58 row_half_mirror row_mask:0xf bank_mask:0xf bound_ctrl:1
	ds_read_b128 v[20:23], v76 offset:36096
	s_nop 0
	v_add_f32_dpp v58, v58, v58 row_mirror row_mask:0xf bank_mask:0xf bound_ctrl:1
	v_pk_fma_f32 v[4:5], v[58:59], v[36:37], v[60:61] op_sel_hi:[0,1,1]
	v_pk_fma_f32 v[6:7], v[58:59], v[38:39], v[62:63] op_sel_hi:[0,1,1]
	s_waitcnt lgkmcnt(6)
	ds_read_b128 v[32:35], v76 offset:28160
	ds_read_b128 v[44:47], v76 offset:40448
	ds_read_b128 v[28:31], v76 offset:24064
	ds_read_b128 v[36:39], v76 offset:32256
	v_pk_mul_f32 v[56:57], v[4:5], v[228:229]
	v_pk_mul_f32 v[64:65], v[4:5], v[40:41]
	v_pk_fma_f32 v[56:57], v[6:7], v[230:231], v[56:57]
	v_pk_fma_f32 v[64:65], v[6:7], v[42:43], v[64:65]
	v_add_f32_e32 v58, v56, v57
	v_pk_mul_f32 v[60:61], v[48:49], v[240:241] op_sel_hi:[0,1]
	v_pk_mul_f32 v[62:63], v[48:49], v[242:243] op_sel_hi:[0,1]
	v_add_f32_dpp v58, v58, v58 quad_perm:[1,0,3,2] row_mask:0xf bank_mask:0xf bound_ctrl:1
	v_pk_fma_f32 v[60:61], v[4:5], v[224:225], v[60:61]
	v_add_f32_e32 v67, v64, v65
	v_add_f32_dpp v58, v58, v58 quad_perm:[2,3,0,1] row_mask:0xf bank_mask:0xf bound_ctrl:1
	v_pk_fma_f32 v[62:63], v[6:7], v[226:227], v[62:63]
	v_add_f32_dpp v71, v66, v66 row_mirror row_mask:0xf bank_mask:0x3
	v_add_f32_dpp v58, v58, v58 row_half_mirror row_mask:0xf bank_mask:0xf bound_ctrl:1
	s_nop 0
	v_add_f32_dpp v71, v67, v67 row_mirror row_mask:0xf bank_mask:0xc
	ds_read_b128 v[40:43], v76 offset:36352
	v_add_f32_dpp v58, v58, v58 row_mirror row_mask:0xf bank_mask:0xf bound_ctrl:1
	v_pk_fma_f32 v[4:5], v[58:59], v[232:233], v[60:61] op_sel_hi:[0,1,1]
	v_pk_fma_f32 v[6:7], v[58:59], v[234:235], v[62:63] op_sel_hi:[0,1,1]
	s_waitcnt lgkmcnt(6)
; DI void scan_task(const Params& p, int l, int isP, int b, int h, int rg, char* smem, const bool dry) {
;     ...
;     for (int s = 0; s < 32; s++) {
;       f32x4 w4n = w4, a4n = a4, b4n = b4;
;       uint2 urn = ur, ukn = uk;
;       float vn = v;
;       if (s < 31) {
;         w4n = *(const f32x4*)(fw + (s + 1) * 64);
;         a4n = *(const f32x4*)(fa + (s + 1) * 64);
;         b4n = *(const f32x4*)(fb + (s + 1) * 64);
;         urn = *(const uint2*)(pr + (s + 1) * 128);
;         ukn = *(const uint2*)(pk + (s + 1) * 128);
;         vn = vb[(s + 1) * 16];
;       }
;       __builtin_amdgcn_sched_barrier(0);
;       const f32x2 klo = {__uint_as_float(uk.x << 16), __uint_as_float(uk.x & 0xFFFF0000u)};
;       const f32x2 khi = {__uint_as_float(uk.y << 16), __uint_as_float(uk.y & 0xFFFF0000u)};
;       const f32x2 rlo = {__uint_as_float(ur.x << 16), __uint_as_float(ur.x & 0xFFFF0000u)};
;       const f32x2 rhi = {__uint_as_float(ur.y << 16), __uint_as_float(ur.y & 0xFFFF0000u)};
;       const f32x2 vv = {v, v};
;       const f32x2 t = Sa * a4.lo + Sb * a4.hi;
;       const f32x2 na = Sa * w4.lo + vv * klo;
;       const f32x2 nb = Sb * w4.hi + vv * khi;
;       float sa = t.x + t.y;
;       float yp = yprev;
;       rowsum16x2(sa, yp);
;       if (s >= 1 && s <= 16) ykeep0 = (jq == s - 1) ? yp : ykeep0;
;       if (s >= 17) ykeep1 = (jq == s - 17) ? yp : ykeep1;
;       const f32x2 sv = {sa, sa};
;       Sa = na + sv * b4.lo;
;       Sb = nb + sv * b4.hi;
;       const f32x2 yy = Sa * rlo + Sb * rhi;
;       yprev = yy.x + yy.y;
;       w4 = w4n; a4 = a4n; b4 = b4n; ur = urn; uk = ukn; v = vn;
;     }
	ds_read_b128 v[228:231], v76 offset:28416
	ds_read_b128 v[240:243], v76 offset:40704
	ds_read_b128 v[224:227], v76 offset:24320
	ds_read_b128 v[232:235], v76 offset:32512
	ds_read_b128 v[52:55], v77 offset:42032
	v_pk_mul_f32 v[56:57], v[4:5], v[12:13]
	v_pk_mul_f32 v[64:65], v[4:5], v[236:237]
	v_pk_fma_f32 v[56:57], v[6:7], v[14:15], v[56:57]
	v_pk_fma_f32 v[64:65], v[6:7], v[238:239], v[64:65]
	v_add_f32_e32 v58, v56, v57
	v_pk_mul_f32 v[60:61], v[48:49], v[24:25] op_sel:[1,0] op_sel_hi:[1,1]
	v_pk_mul_f32 v[62:63], v[48:49], v[26:27] op_sel:[1,0] op_sel_hi:[1,1]
	v_add_f32_dpp v58, v58, v58 quad_perm:[1,0,3,2] row_mask:0xf bank_mask:0xf bound_ctrl:1
	v_pk_fma_f32 v[60:61], v[4:5], v[8:9], v[60:61]
	v_add_f32_e32 v66, v64, v65
	v_add_f32_dpp v58, v58, v58 quad_perm:[2,3,0,1] row_mask:0xf bank_mask:0xf bound_ctrl:1
	v_pk_fma_f32 v[62:63], v[6:7], v[10:11], v[62:63]
	v_add_f32_dpp v70, v70, v70 row_half_mirror row_mask:0xf bank_mask:0x5
	v_add_f32_dpp v58, v58, v58 row_half_mirror row_mask:0xf bank_mask:0xf bound_ctrl:1
	s_nop 0
	v_add_f32_dpp v70, v71, v71 row_half_mirror row_mask:0xf bank_mask:0xa
	ds_read_b128 v[236:239], v76 offset:36608
	v_add_f32_dpp v58, v58, v58 row_mirror row_mask:0xf bank_mask:0xf bound_ctrl:1
	v_pk_fma_f32 v[4:5], v[58:59], v[16:17], v[60:61] op_sel_hi:[0,1,1]
	v_pk_fma_f32 v[6:7], v[58:59], v[18:19], v[62:63] op_sel_hi:[0,1,1]
	s_waitcnt lgkmcnt(7)
	ds_read_b128 v[12:15], v76 offset:28672
	ds_read_b128 v[24:27], v76 offset:40960
	ds_read_b128 v[8:11], v76 offset:24576
	ds_read_b128 v[16:19], v76 offset:32768
	v_pk_mul_f32 v[56:57], v[4:5], v[32:33]
	v_pk_mul_f32 v[64:65], v[4:5], v[20:21]
	v_pk_fma_f32 v[56:57], v[6:7], v[34:35], v[56:57]
	v_pk_fma_f32 v[64:65], v[6:7], v[22:23], v[64:65]
	v_add_f32_e32 v58, v56, v57
	v_pk_mul_f32 v[60:61], v[50:51], v[44:45] op_sel_hi:[0,1]
	v_pk_mul_f32 v[62:63], v[50:51], v[46:47] op_sel_hi:[0,1]
	v_add_f32_dpp v58, v58, v58 quad_perm:[1,0,3,2] row_mask:0xf bank_mask:0xf bound_ctrl:1
	v_pk_fma_f32 v[60:61], v[4:5], v[28:29], v[60:61]
	v_add_f32_e32 v67, v64, v65
	v_add_f32_dpp v58, v58, v58 quad_perm:[2,3,0,1] row_mask:0xf bank_mask:0xf bound_ctrl:1
	v_pk_fma_f32 v[62:63], v[6:7], v[30:31], v[62:63]
	v_add_f32_dpp v72, v66, v66 row_mirror row_mask:0xf bank_mask:0x3
	v_add_f32_dpp v58, v58, v58 row_half_mirror row_mask:0xf bank_mask:0xf bound_ctrl:1
	s_nop 0
	v_add_f32_dpp v72, v67, v67 row_mirror row_mask:0xf bank_mask:0xc
	ds_read_b128 v[20:23], v76 offset:36864
	v_add_f32_dpp v58, v58, v58 row_mirror row_mask:0xf bank_mask:0xf bound_ctrl:1
	v_pk_fma_f32 v[4:5], v[58:59], v[36:37], v[60:61] op_sel_hi:[0,1,1]
	v_pk_fma_f32 v[6:7], v[58:59], v[38:39], v[62:63] op_sel_hi:[0,1,1]
	s_waitcnt lgkmcnt(7)
	ds_read_b128 v[32:35], v76 offset:28928
	ds_read_b128 v[44:47], v76 offset:41216
	ds_read_b128 v[28:31], v76 offset:24832
	ds_read_b128 v[36:39], v76 offset:33024
	v_pk_mul_f32 v[56:57], v[4:5], v[228:229]
	v_pk_mul_f32 v[64:65], v[4:5], v[40:41]
	v_pk_fma_f32 v[56:57], v[6:7], v[230:231], v[56:57]
	v_pk_fma_f32 v[64:65], v[6:7], v[42:43], v[64:65]
	v_add_f32_e32 v58, v56, v57
	v_pk_mul_f32 v[60:61], v[50:51], v[240:241] op_sel:[1,0] op_sel_hi:[1,1]
	v_pk_mul_f32 v[62:63], v[50:51], v[242:243] op_sel:[1,0] op_sel_hi:[1,1]
	v_add_f32_dpp v58, v58, v58 quad_perm:[1,0,3,2] row_mask:0xf bank_mask:0xf bound_ctrl:1
	v_pk_fma_f32 v[60:61], v[4:5], v[224:225], v[60:61]
	v_add_f32_e32 v66, v64, v65
	v_add_f32_dpp v58, v58, v58 quad_perm:[2,3,0,1] row_mask:0xf bank_mask:0xf bound_ctrl:1
	v_pk_fma_f32 v[62:63], v[6:7], v[226:227], v[62:63]
	s_nop 0
	v_add_f32_dpp v58, v58, v58 row_half_mirror row_mask:0xf bank_mask:0xf bound_ctrl:1
	ds_read_b128 v[40:43], v76 offset:37120
	s_nop 0
	v_add_f32_dpp v58, v58, v58 row_mirror row_mask:0xf bank_mask:0xf bound_ctrl:1
	v_pk_fma_f32 v[4:5], v[58:59], v[232:233], v[60:61] op_sel_hi:[0,1,1]
	v_pk_fma_f32 v[6:7], v[58:59], v[234:235], v[62:63] op_sel_hi:[0,1,1]
	s_waitcnt lgkmcnt(6)
; DI void scan_task(const Params& p, int l, int isP, int b, int h, int rg, char* smem, const bool dry) {
;     ...
;     for (int s = 0; s < 32; s++) {
;       f32x4 w4n = w4, a4n = a4, b4n = b4;
;       uint2 urn = ur, ukn = uk;
;       float vn = v;
;       if (s < 31) {
;         w4n = *(const f32x4*)(fw + (s + 1) * 64);
;         a4n = *(const f32x4*)(fa + (s + 1) * 64);
;         b4n = *(const f32x4*)(fb + (s + 1) * 64);
;         urn = *(const uint2*)(pr + (s + 1) * 128);
;         ukn = *(const uint2*)(pk + (s + 1) * 128);
;         vn = vb[(s + 1) * 16];
;       }
;       __builtin_amdgcn_sched_barrier(0);
;       const f32x2 klo = {__uint_as_float(uk.x << 16), __uint_as_float(uk.x & 0xFFFF0000u)};
;       const f32x2 khi = {__uint_as_float(uk.y << 16), __uint_as_float(uk.y & 0xFFFF0000u)};
;       const f32x2 rlo = {__uint_as_float(ur.x << 16), __uint_as_float(ur.x & 0xFFFF0000u)};
;       const f32x2 rhi = {__uint_as_float(ur.y << 16), __uint_as_float(ur.y & 0xFFFF0000u)};
;       const f32x2 vv = {v, v};
;       const f32x2 t = Sa * a4.lo + Sb * a4.hi;
;       const f32x2 na = Sa * w4.lo + vv * klo;
;       const f32x2 nb = Sb * w4.hi + vv * khi;
;       float sa = t.x + t.y;
;       float yp = yprev;
;       rowsum16x2(sa, yp);
;       if (s >= 1 && s <= 16) ykeep0 = (jq == s - 1) ? yp : ykeep0;
;       if (s >= 17) ykeep1 = (jq == s - 17) ? yp : ykeep1;
;       const f32x2 sv = {sa, sa};
;       Sa = na + sv * b4.lo;
;       Sb = nb + sv * b4.hi;
;       const f32x2 yy = Sa * rlo + Sb * rhi;
;       yprev = yy.x + yy.y;
;       w4 = w4n; a4 = a4n; b4 = b4n; ur = urn; uk = ukn; v = vn;
;     }
;     {
;       const float yl = rowsum16(yprev);
;       ykeep1 = (jq == 15) ? yl : ykeep1;
;     }
;     if (!dry) { yo[0] = ykeep0; yo[(size_t)16 * 512] = ykeep1; }
;     if (more) sstore((c + 1) & 1);
;     __syncthreads();
	ds_read_b128 v[228:231], v76 offset:29184
	ds_read_b128 v[240:243], v76 offset:41472
	ds_read_b128 v[224:227], v76 offset:25088
	ds_read_b128 v[232:235], v76 offset:33280
	v_pk_mul_f32 v[56:57], v[4:5], v[12:13]
	v_pk_mul_f32 v[64:65], v[4:5], v[236:237]
	v_pk_fma_f32 v[56:57], v[6:7], v[14:15], v[56:57]
	v_pk_fma_f32 v[64:65], v[6:7], v[238:239], v[64:65]
	v_add_f32_e32 v58, v56, v57
	v_pk_mul_f32 v[60:61], v[52:53], v[24:25] op_sel_hi:[0,1]
	v_pk_mul_f32 v[62:63], v[52:53], v[26:27] op_sel_hi:[0,1]
	v_add_f32_dpp v58, v58, v58 quad_perm:[1,0,3,2] row_mask:0xf bank_mask:0xf bound_ctrl:1
	v_pk_fma_f32 v[60:61], v[4:5], v[8:9], v[60:61]
	v_add_f32_e32 v67, v64, v65
	v_add_f32_dpp v58, v58, v58 quad_perm:[2,3,0,1] row_mask:0xf bank_mask:0xf bound_ctrl:1
	v_pk_fma_f32 v[62:63], v[6:7], v[10:11], v[62:63]
	v_add_f32_dpp v73, v66, v66 row_mirror row_mask:0xf bank_mask:0x3
	v_add_f32_dpp v58, v58, v58 row_half_mirror row_mask:0xf bank_mask:0xf bound_ctrl:1
	s_nop 0
	v_add_f32_dpp v73, v67, v67 row_mirror row_mask:0xf bank_mask:0xc
	ds_read_b128 v[236:239], v76 offset:37376
	v_add_f32_dpp v58, v58, v58 row_mirror row_mask:0xf bank_mask:0xf bound_ctrl:1
	v_pk_fma_f32 v[4:5], v[58:59], v[16:17], v[60:61] op_sel_hi:[0,1,1]
	v_pk_fma_f32 v[6:7], v[58:59], v[18:19], v[62:63] op_sel_hi:[0,1,1]
	s_waitcnt lgkmcnt(6)
	ds_read_b128 v[12:15], v76 offset:29440
	ds_read_b128 v[24:27], v76 offset:41728
	ds_read_b128 v[8:11], v76 offset:25344
	ds_read_b128 v[16:19], v76 offset:33536
	v_pk_mul_f32 v[56:57], v[4:5], v[32:33]
	v_pk_mul_f32 v[64:65], v[4:5], v[20:21]
	v_pk_fma_f32 v[56:57], v[6:7], v[34:35], v[56:57]
	v_pk_fma_f32 v[64:65], v[6:7], v[22:23], v[64:65]
	v_add_f32_e32 v58, v56, v57
	v_pk_mul_f32 v[60:61], v[52:53], v[44:45] op_sel:[1,0] op_sel_hi:[1,1]
	v_pk_mul_f32 v[62:63], v[52:53], v[46:47] op_sel:[1,0] op_sel_hi:[1,1]
	v_add_f32_dpp v58, v58, v58 quad_perm:[1,0,3,2] row_mask:0xf bank_mask:0xf bound_ctrl:1
	v_pk_fma_f32 v[60:61], v[4:5], v[28:29], v[60:61]
	v_add_f32_e32 v66, v64, v65
	v_add_f32_dpp v58, v58, v58 quad_perm:[2,3,0,1] row_mask:0xf bank_mask:0xf bound_ctrl:1
	v_pk_fma_f32 v[62:63], v[6:7], v[30:31], v[62:63]
	v_add_f32_dpp v72, v72, v72 row_half_mirror row_mask:0xf bank_mask:0x5
	v_add_f32_dpp v58, v58, v58 row_half_mirror row_mask:0xf bank_mask:0xf bound_ctrl:1
	s_nop 0
	v_add_f32_dpp v72, v73, v73 row_half_mirror row_mask:0xf bank_mask:0xa
	ds_read_b128 v[20:23], v76 offset:37632
	v_add_f32_dpp v58, v58, v58 row_mirror row_mask:0xf bank_mask:0xf bound_ctrl:1
	v_pk_fma_f32 v[4:5], v[58:59], v[36:37], v[60:61] op_sel_hi:[0,1,1]
	v_pk_fma_f32 v[6:7], v[58:59], v[38:39], v[62:63] op_sel_hi:[0,1,1]
	s_waitcnt lgkmcnt(6)
	v_pk_mul_f32 v[56:57], v[4:5], v[228:229]
	v_pk_mul_f32 v[64:65], v[4:5], v[40:41]
	v_pk_fma_f32 v[56:57], v[6:7], v[230:231], v[56:57]
	v_pk_fma_f32 v[64:65], v[6:7], v[42:43], v[64:65]
	v_add_f32_e32 v58, v56, v57
	v_pk_mul_f32 v[60:61], v[54:55], v[240:241] op_sel_hi:[0,1]
	v_pk_mul_f32 v[62:63], v[54:55], v[242:243] op_sel_hi:[0,1]
	v_add_f32_dpp v58, v58, v58 quad_perm:[1,0,3,2] row_mask:0xf bank_mask:0xf bound_ctrl:1
	v_pk_fma_f32 v[60:61], v[4:5], v[224:225], v[60:61]
	v_add_f32_e32 v67, v64, v65
	v_add_f32_dpp v58, v58, v58 quad_perm:[2,3,0,1] row_mask:0xf bank_mask:0xf bound_ctrl:1
	v_pk_fma_f32 v[62:63], v[6:7], v[226:227], v[62:63]
	v_add_f32_dpp v74, v66, v66 row_mirror row_mask:0xf bank_mask:0x3
	v_add_f32_dpp v58, v58, v58 row_half_mirror row_mask:0xf bank_mask:0xf bound_ctrl:1
	s_nop 0
	v_add_f32_dpp v74, v67, v67 row_mirror row_mask:0xf bank_mask:0xc
	v_add_f32_dpp v58, v58, v58 row_mirror row_mask:0xf bank_mask:0xf bound_ctrl:1
	v_pk_fma_f32 v[4:5], v[58:59], v[232:233], v[60:61] op_sel_hi:[0,1,1]
	v_pk_fma_f32 v[6:7], v[58:59], v[234:235], v[62:63] op_sel_hi:[0,1,1]
	s_waitcnt lgkmcnt(1)
	v_pk_mul_f32 v[56:57], v[4:5], v[12:13]
	v_pk_mul_f32 v[64:65], v[4:5], v[236:237]
	v_pk_fma_f32 v[56:57], v[6:7], v[14:15], v[56:57]
	v_pk_fma_f32 v[64:65], v[6:7], v[238:239], v[64:65]
	v_add_f32_e32 v58, v56, v57
	v_pk_mul_f32 v[60:61], v[54:55], v[24:25] op_sel:[1,0] op_sel_hi:[1,1]
	v_pk_mul_f32 v[62:63], v[54:55], v[26:27] op_sel:[1,0] op_sel_hi:[1,1]
	v_add_f32_dpp v58, v58, v58 quad_perm:[1,0,3,2] row_mask:0xf bank_mask:0xf bound_ctrl:1
	v_pk_fma_f32 v[60:61], v[4:5], v[8:9], v[60:61]
	v_add_f32_e32 v66, v64, v65
	v_add_f32_dpp v58, v58, v58 quad_perm:[2,3,0,1] row_mask:0xf bank_mask:0xf bound_ctrl:1
	v_pk_fma_f32 v[62:63], v[6:7], v[10:11], v[62:63]
	s_nop 0
	v_add_f32_dpp v58, v58, v58 row_half_mirror row_mask:0xf bank_mask:0xf bound_ctrl:1
	s_nop 1
	v_add_f32_dpp v58, v58, v58 row_mirror row_mask:0xf bank_mask:0xf bound_ctrl:1
	v_pk_fma_f32 v[4:5], v[58:59], v[16:17], v[60:61] op_sel_hi:[0,1,1]
	v_pk_fma_f32 v[6:7], v[58:59], v[18:19], v[62:63] op_sel_hi:[0,1,1]
	s_waitcnt lgkmcnt(0)
	v_pk_mul_f32 v[64:65], v[4:5], v[20:21]
	v_pk_fma_f32 v[64:65], v[6:7], v[22:23], v[64:65]
	v_add_f32_e32 v67, v64, v65
	s_add_i32 s23, s16, 2
	s_cmp_lt_u32 s23, s17
	s_cbranch_scc0 .Lscan_lastB
	s_cmp_lg_u32 s22, 0
	s_cbranch_scc1 .Lscan_w6B
	s_waitcnt vmcnt(0)
	s_branch .Lscan_wdB

; DI void scan_task(const Params& p, int l, int isP, int b, int h, int rg, char* smem, const bool dry) {
;     ...
;   auto gload = [&](int c) {
;     const int tk = tokbase + c * 32;
;     rd0 = *(const float4*)(p.R + (size_t)(tk + ds) * RS + h * 64 + dj * 4);
;     rd1 = *(const float4*)(p.R + (size_t)(tk + 16 + ds) * RS + h * 64 + dj * 4);
;     const bf16_t* rb = (const bf16_t*)(p.R + (size_t)(tk + lst) * RS + 512) + h * 64 + lch * 8;
;     qr = *(const uint4*)(rb);
;     qk = *(const uint4*)(rb + 512);
;     qa = *(const uint4*)(rb + 1536);
;     qb = *(const uint4*)(rb + 2048);
;     if (tid < 64) {
;       const int s = tid >> 1, half = tid & 1;
;       rv = *(const uint4*)((const bf16_t*)(p.R + (size_t)(tk + s) * RS + 512) + 1024 + h * 64 + rg * 16 + half * 8);
;     }
;   };
;     ...
;   auto sstore = [&](int bi) {
;     char* bb = smem + bi * BUFB;
;     *(float4*)(bb + (ds * 64 + dj * 4) * 4) = rd0;
;     *(float4*)(bb + ((16 + ds) * 64 + dj * 4) * 4) = rd1;
;     {
;       CVT8(qa, alo, ahi)
;       float* d = (float*)(bb + 8192) + lst * 64 + lch * 8;
;       *(float4*)d = alo; *(float4*)(d + 4) = ahi;
;     }
;     {
;       CVT8(qb, blo, bhi)
;       float* d = (float*)(bb + 16384) + lst * 64 + lch * 8;
;       *(float4*)d = blo; *(float4*)(d + 4) = bhi;
;     }
;     *(uint4*)(bb + 24576 + (lst * 64 + lch * 8) * 2) = qr;
;     *(uint4*)(bb + 28672 + (lst * 64 + lch * 8) * 2) = qk;
;     if (tid < 64) {
;       const int s = tid >> 1, half = tid & 1;
;       CVT8(rv, vlo, vhi)
;       float* d = (float*)(bb + 32768) + s * 16 + half * 8;
;       *(float4*)d = vlo; *(float4*)(d + 4) = vhi;
;     }
;   };
.Lscan_wdB:
	ds_write_b128 v78, v[84:87] offset:0
	v_lshlrev_b32_e32 v8, 16, v92
	v_and_b32_e32 v9, 0xffff0000, v92
	v_lshlrev_b32_e32 v10, 16, v93
	v_and_b32_e32 v11, 0xffff0000, v93
	ds_write_b128 v78, v[8:11] offset:4096
	v_lshlrev_b32_e32 v12, 16, v94
	v_and_b32_e32 v13, 0xffff0000, v94
	v_lshlrev_b32_e32 v14, 16, v95
	v_and_b32_e32 v15, 0xffff0000, v95
	ds_write_b128 v78, v[12:15] offset:8192
	v_lshlrev_b32_e32 v16, 16, v88
	v_and_b32_e32 v17, 0xffff0000, v88
	v_lshlrev_b32_e32 v18, 16, v89
	v_and_b32_e32 v19, 0xffff0000, v89
	ds_write_b128 v78, v[16:19] offset:12288
	v_lshlrev_b32_e32 v20, 16, v90
	v_and_b32_e32 v21, 0xffff0000, v90
	v_lshlrev_b32_e32 v22, 16, v91
	v_and_b32_e32 v23, 0xffff0000, v91
	ds_write_b128 v78, v[20:23] offset:16384
	v_lshlrev_b32_e32 v24, 16, v96
	ds_write_b32 v79, v24 offset:20480
	s_add_i32 s23, s16, 4
	s_cmp_lt_u32 s23, s17
	s_cselect_b32 s22, 1, 0
	s_cbranch_scc0 .Lscan_noldB
	global_load_dwordx4 v[84:87], v80, s[12:13]
	global_load_dwordx2 v[88:89], v81, s[12:13] offset:-1024
	global_load_dwordx2 v[90:91], v81, s[12:13]
	global_load_dwordx2 v[92:93], v81, s[12:13] offset:2048
	global_load_dwordx2 v[94:95], v81, s[12:13] offset:3072
	global_load_ushort v96, v82, s[12:13]
	s_add_u32 s12, s12, 0x1c000
	s_addc_u32 s13, s13, 0
